# v87 + one static s_setprio 1 only for blocks >= gridDim/2 (the younger co-resident workgroup) in the GEMM main loops, none for the others
# speedup vs baseline: 1.0012x; 1.0012x over previous
.LBB1_54:
	v_readlane_b32 s4, v242, 0
	s_lshl_b32 s5, s2, 3
	s_and_b32 s6, s4, 7
	s_or_b32 s5, s6, s5
	s_mul_i32 s5, s5, s55
	s_ashr_i32 s4, s4, 3
	s_add_i32 s4, s5, s4
	s_cmpk_lt_i32 s4, 0x400
	s_mov_b64 s[40:41], -1
	s_cbranch_scc0 .LBB1_53
	s_ashr_i32 s5, s4, 31
	s_lshr_b32 s5, s5, 25
	s_add_i32 s5, s4, s5
	s_and_b32 s6, s5, 0xffffff80
	s_sub_i32 s7, s4, s6
	s_ashr_i32 s4, s7, 31
	s_lshr_b32 s4, s4, 29
	s_add_i32 s6, s7, s4
	s_and_b32 s4, s6, 0xfffff8
	s_sub_i32 s4, s7, s4
	s_lshl_b32 s5, s5, 4
	s_and_b32 s5, s5, 0xfffff800
	s_lshl_b32 s4, s4, 8
	s_add_i32 s4, s4, s5
	s_lshl_b32 s5, s6, 4
	v_mov_b32_e32 v134, v162
	s_and_b32 s40, s5, 0xffffff80
	s_movk_i32 s10, 0x78
	v_readfirstlane_b32 s5, v134
	v_lshrrev_b32_e32 v0, 3, v134
	v_and_b32_e32 v0, 6, v0
	s_and_b32 s8, s5, 0xffffffc0
	s_waitcnt lgkmcnt(0)
	v_bfe_u32 v2, v134, 2, 4
	v_lshrrev_b32_e64 v0, v0, s10
	s_add_i32 s8, s8, s4
	v_xor_b32_e32 v3, v0, v134
	v_or_b32_e32 v0, s8, v2
	v_ashrrev_i32_e32 v1, 31, v0
	v_lshlrev_b64 v[0:1], 11, v[0:1]
	v_lshlrev_b32_e32 v3, 4, v3
	v_lshl_add_u64 v[0:1], s[74:75], 0, v[0:1]
	v_and_b32_e32 v128, 48, v3
	s_load_dwordx16 s[80:95], s[0:1], 0xc0
	s_ashr_i32 s6, s5, 6
	v_lshl_add_u64 v[130:131], v[0:1], 0, v[128:129]
	v_or_b32_e32 v0, s40, v2
	v_lshl_add_u32 v0, s6, 5, v0
	v_ashrrev_i32_e32 v1, 31, v0
	v_lshlrev_b64 v[0:1], 11, v[0:1]
	s_waitcnt lgkmcnt(0)
	v_lshl_add_u64 v[0:1], s[92:93], 0, v[0:1]
	v_lshl_add_u64 v[132:133], v[0:1], 0, v[128:129]
	v_lshrrev_b32_e32 v0, 1, v134
	v_and_b32_e32 v0, 6, v0
	v_bfe_u32 v136, v134, 4, 2
	s_lshl_b32 s8, s6, 12
	v_lshrrev_b32_e64 v0, v0, s10
	v_and_b32_e32 v135, 15, v134
	s_lshl_b32 s9, s6, 11
	s_and_b32 s6, s5, 0xffffff80
	v_bitop3_b32 v0, v0, v136, 3 bitop3:0x6c
	s_and_b32 s5, s5, 64
	s_add_i32 s10, s8, 16
	v_lshlrev_b32_e32 v138, 4, v0
	v_or_b32_e32 v0, s5, v135
	s_mov_b32 m0, s10
	v_lshlrev_b32_e32 v139, 6, v0
	s_barrier
	v_lshl_add_u64 v[0:1], v[130:131], 0, s[34:35]
	s_add_i32 m0, s10, 0x400
	s_mov_b64 s[12:13], 0x10000
	v_lshl_add_u64 v[0:1], v[130:131], 0, s[12:13]
	s_add_i32 m0, s10, 0x800
	s_mov_b64 s[12:13], 0x18000
	v_lshl_add_u64 v[0:1], v[130:131], 0, s[12:13]
	s_add_i32 m0, s10, 0xc00
	s_sub_i32 s11, s10, s9
	s_add_i32 m0, s11, 0x4000
	v_lshl_add_u64 v[0:1], v[132:133], 0, s[34:35]
	s_add_i32 m0, s11, 0x4400
	s_mov_b64 s[12:13], 0x8040
	v_lshl_add_u64 v[0:1], v[130:131], 0, 64
	s_add_i32 m0, s10, 0x6000
	s_mov_b64 s[14:15], 0x10040
	v_lshl_add_u64 v[0:1], v[130:131], 0, s[12:13]
	s_add_i32 m0, s10, 0x6400
	v_or_b32_e32 v128, s6, v135
	v_lshl_add_u64 v[0:1], v[130:131], 0, s[14:15]
	s_add_i32 m0, s10, 0x6800
	s_mov_b64 s[14:15], 0x18040
	v_lshl_add_u64 v[0:1], v[130:131], 0, s[14:15]
	s_add_i32 m0, s10, 0x6c00
	v_lshlrev_b32_e32 v137, 6, v128
	v_lshl_add_u64 v[0:1], v[132:133], 0, 64
	s_add_i32 m0, s11, 0xa000
	s_mov_b32 s10, 0
	v_lshl_add_u64 v[0:1], v[132:133], 0, s[12:13]
	s_add_i32 m0, s11, 0xa400
	s_mov_b32 s11, 0
	v_mov_b32_e32 v0, 0
	v_mov_b32_e32 v1, v0
	v_mov_b32_e32 v2, v0
	v_mov_b32_e32 v3, v0
	v_mov_b32_e32 v4, v0
	v_mov_b32_e32 v5, v0
	v_mov_b32_e32 v6, v0
	v_mov_b32_e32 v7, v0
	v_mov_b32_e32 v8, v0
	v_mov_b32_e32 v9, v0
	v_mov_b32_e32 v10, v0
	v_mov_b32_e32 v11, v0
	v_mov_b32_e32 v12, v0
	v_mov_b32_e32 v13, v0
	v_mov_b32_e32 v14, v0
	v_mov_b32_e32 v15, v0
	v_mov_b32_e32 v16, v0
	v_mov_b32_e32 v17, v0
	v_mov_b32_e32 v18, v0
	v_mov_b32_e32 v19, v0
	v_mov_b32_e32 v20, v0
	v_mov_b32_e32 v21, v0
	v_mov_b32_e32 v22, v0
	v_mov_b32_e32 v23, v0
	v_mov_b32_e32 v24, v0
	v_mov_b32_e32 v25, v0
	v_mov_b32_e32 v26, v0
	v_mov_b32_e32 v27, v0
	v_mov_b32_e32 v28, v0
	v_mov_b32_e32 v29, v0
	v_mov_b32_e32 v30, v0
	v_mov_b32_e32 v31, v0
	v_mov_b32_e32 v32, v0
	v_mov_b32_e32 v33, v0
	v_mov_b32_e32 v34, v0
	v_mov_b32_e32 v35, v0
	v_mov_b32_e32 v36, v0
	v_mov_b32_e32 v37, v0
	v_mov_b32_e32 v38, v0
	v_mov_b32_e32 v39, v0
	v_mov_b32_e32 v40, v0
	v_mov_b32_e32 v41, v0
	v_mov_b32_e32 v42, v0
	v_mov_b32_e32 v43, v0
	v_mov_b32_e32 v44, v0
	v_mov_b32_e32 v45, v0
	v_mov_b32_e32 v46, v0
	v_mov_b32_e32 v47, v0
	v_mov_b32_e32 v48, v0
	v_mov_b32_e32 v49, v0
	v_mov_b32_e32 v50, v0
	v_mov_b32_e32 v51, v0
	v_mov_b32_e32 v52, v0
	v_mov_b32_e32 v53, v0
	v_mov_b32_e32 v54, v0
	v_mov_b32_e32 v55, v0
	v_mov_b32_e32 v56, v0
	v_mov_b32_e32 v57, v0
	v_mov_b32_e32 v58, v0
	v_mov_b32_e32 v59, v0
	v_mov_b32_e32 v60, v0
	v_mov_b32_e32 v61, v0
	v_mov_b32_e32 v62, v0
	v_mov_b32_e32 v63, v0
	v_mov_b32_e32 v64, v0
	v_mov_b32_e32 v65, v0
	v_mov_b32_e32 v66, v0
	v_mov_b32_e32 v67, v0
	v_mov_b32_e32 v68, v0
	v_mov_b32_e32 v69, v0
	v_mov_b32_e32 v70, v0
	v_mov_b32_e32 v71, v0
	v_mov_b32_e32 v72, v0
	v_mov_b32_e32 v73, v0
	v_mov_b32_e32 v74, v0
	v_mov_b32_e32 v75, v0
	v_mov_b32_e32 v84, v0
	v_mov_b32_e32 v85, v0
	v_mov_b32_e32 v86, v0
	v_mov_b32_e32 v87, v0
	v_mov_b32_e32 v96, v0
	v_mov_b32_e32 v97, v0
	v_mov_b32_e32 v98, v0
	v_mov_b32_e32 v99, v0
	v_mov_b32_e32 v100, v0
	v_mov_b32_e32 v101, v0
	v_mov_b32_e32 v102, v0
	v_mov_b32_e32 v103, v0
	v_mov_b32_e32 v104, v0
	v_mov_b32_e32 v105, v0
	v_mov_b32_e32 v106, v0
	v_mov_b32_e32 v107, v0
	v_mov_b32_e32 v108, v0
	v_mov_b32_e32 v109, v0
	v_mov_b32_e32 v110, v0
	v_mov_b32_e32 v111, v0
	v_mov_b32_e32 v112, v0
	v_mov_b32_e32 v113, v0
	v_mov_b32_e32 v114, v0
	v_mov_b32_e32 v115, v0
	v_mov_b32_e32 v116, v0
	v_mov_b32_e32 v117, v0
	v_mov_b32_e32 v118, v0
	v_mov_b32_e32 v119, v0
	v_mov_b32_e32 v120, v0
	v_mov_b32_e32 v121, v0
	v_mov_b32_e32 v122, v0
	v_mov_b32_e32 v123, v0
	v_mov_b32_e32 v124, v0
	v_mov_b32_e32 v125, v0
	v_mov_b32_e32 v126, v0
	v_mov_b32_e32 v127, v0
	v_mov_b32_e32 v76, v0
	v_mov_b32_e32 v77, v0
	v_mov_b32_e32 v78, v0
	v_mov_b32_e32 v79, v0
	v_mov_b32_e32 v80, v0
	v_mov_b32_e32 v81, v0
	v_mov_b32_e32 v82, v0
	v_mov_b32_e32 v83, v0
	v_mov_b32_e32 v88, v0
	v_mov_b32_e32 v89, v0
	v_mov_b32_e32 v90, v0
	v_mov_b32_e32 v91, v0
	v_mov_b32_e32 v92, v0
	v_mov_b32_e32 v93, v0
	v_mov_b32_e32 v94, v0
	v_mov_b32_e32 v95, v0
	s_mov_b64 s[16:17], 0x10080
	v_and_b32_e32 v204, 15, v168
	v_lshrrev_b32_e32 v205, 4, v168
	v_bfe_u32 v206, v168, 1, 3
	v_xor_b32_e32 v205, v205, v206
	v_lshlrev_b32_e32 v205, 4, v205
	v_readfirstlane_b32 s15, v162
	v_readfirstlane_b32 s18, v130
	v_readfirstlane_b32 s19, v131
	v_readfirstlane_b32 s28, v132
	v_readfirstlane_b32 s29, v133
	s_lshr_b32 s15, s15, 6
	s_lshl_b32 s54, s15, 12
	s_lshr_b32 s41, s15, 1
	s_and_b32 s42, s15, 1
	v_lshl_add_u32 v206, s41, 6, v204
	v_lshl_add_u32 v196, v206, 7, v205
	v_xor_b32_e32 v197, 64, v196
	v_lshl_add_u32 v206, s42, 6, v204
	v_lshl_add_u32 v198, v206, 7, v205
	v_xor_b32_e32 v199, 64, v198
	v_add_u32_e32 v198, 0xc010, v198
	v_add_u32_e32 v199, 0xc010, v199
	v_lshrrev_b32_e32 v206, 3, v168
	v_and_b32_e32 v207, 7, v168
	v_lshrrev_b32_e32 v204, 1, v206
	v_xor_b32_e32 v207, v207, v204
	v_lshlrev_b32_e32 v207, 4, v207
	v_lshl_add_u32 v200, v206, 11, v207
	v_xor_b32_e32 v201, 64, v200
	s_lshl_b32 s42, s42, 16
	s_sub_u32 s18, s18, s42
	s_subb_u32 s19, s19, 0
	s_add_i32 s41, s54, 16
	s_add_i32 m0, s41, 0x0
	s_nop 0
	global_load_lds_dwordx4 v200, s[18:19]
	s_add_i32 m0, s41, 0x400
	s_add_u32 s52, s18, 0x4000
	s_addc_u32 s53, s19, 0
	global_load_lds_dwordx4 v201, s[52:53]
	s_add_i32 m0, s41, 0x800
	s_add_u32 s52, s18, 0x8000
	s_addc_u32 s53, s19, 0
	global_load_lds_dwordx4 v200, s[52:53]
	s_add_i32 m0, s41, 0xc00
	s_add_u32 s52, s18, 0xc000
	s_addc_u32 s53, s19, 0
	global_load_lds_dwordx4 v201, s[52:53]
	s_add_i32 m0, s54, 0xc010
	s_nop 0
	global_load_lds_dwordx4 v200, s[28:29]
	s_add_i32 m0, s54, 0xc410
	s_add_u32 s52, s28, 0x4000
	s_addc_u32 s53, s29, 0
	global_load_lds_dwordx4 v201, s[52:53]
	s_add_i32 m0, s54, 0xc810
	s_add_u32 s52, s28, 0x8000
	s_addc_u32 s53, s29, 0
	global_load_lds_dwordx4 v200, s[52:53]
	s_add_i32 m0, s54, 0xcc10
	s_add_u32 s52, s28, 0xc000
	s_addc_u32 s53, s29, 0
	global_load_lds_dwordx4 v201, s[52:53]
	s_add_u32 s50, s18, 0x20000
	s_addc_u32 s51, s19, 0
	s_add_i32 m0, s41, 0x4000
	s_nop 0
	global_load_lds_dwordx4 v200, s[50:51]
	s_add_i32 m0, s41, 0x4400
	s_add_u32 s52, s50, 0x4000
	s_addc_u32 s53, s51, 0
	global_load_lds_dwordx4 v201, s[52:53]
	s_add_i32 m0, s41, 0x4800
	s_add_u32 s52, s50, 0x8000
	s_addc_u32 s53, s51, 0
	global_load_lds_dwordx4 v200, s[52:53]
	s_add_i32 m0, s41, 0x4c00
	s_add_u32 s52, s50, 0xc000
	s_addc_u32 s53, s51, 0
	global_load_lds_dwordx4 v201, s[52:53]
	s_mov_b32 s13, 0
	s_mov_b32 s14, 0
	v_readlane_b32 s15, v242, 0
	v_readlane_b32 s41, v241, 24
	s_nop 3
	s_lshr_b32 s41, s41, 3
	s_cmp_ge_u32 s15, s41
	s_cbranch_scc0 .Lprio_done_LBB1_56
	s_setprio 1
.Lprio_done_LBB1_56:
.LBB1_56:
	s_mul_i32 s15, s13, 0x4000
	s_add_i32 s15, s15, 16
	s_add_i32 s41, s13, 2
	s_cmp_ge_u32 s41, 3
	s_cselect_b32 s42, 3, 0
	s_sub_i32 s41, s41, s42
	s_mul_i32 s41, s41, 0x4000
	s_add_i32 s41, s41, 16
	s_add_i32 s41, s41, s54
	s_add_i32 s32, s14, 1
	s_min_u32 s32, s32, 15
	s_lshl_b32 s32, s32, 7
	s_add_u32 s50, s18, s32
	s_addc_u32 s51, s19, 0
	s_waitcnt vmcnt(4)
	s_barrier
	v_add_u32_e32 v202, s15, v196
	v_add_u32_e32 v203, s15, v197
	ds_read_b128 v[140:143], v198 offset:0
	ds_read_b128 v[144:147], v198 offset:2048
	ds_read_b128 v[148:151], v198 offset:4096
	ds_read_b128 v[152:155], v198 offset:6144
	ds_read_b128 v[156:159], v202
	ds_read_b128 v[216:219], v199 offset:0
	ds_read_b128 v[220:223], v199 offset:2048
	ds_read_b128 v[224:227], v199 offset:4096
	ds_read_b128 v[228:231], v199 offset:6144
	ds_read_b128 v[188:191], v203
	ds_read_b128 v[192:195], v202 offset:2048
	ds_read_b128 v[208:211], v203 offset:2048
	s_waitcnt lgkmcnt(7)
	s_add_i32 m0, s41, 0x0
	v_mfma_f32_16x16x32_bf16 v[124:127], v[140:143], v[156:159], v[124:127]
	v_mfma_f32_16x16x32_bf16 v[120:123], v[144:147], v[156:159], v[120:123]
	v_mfma_f32_16x16x32_bf16 v[116:119], v[148:151], v[156:159], v[116:119]
	v_mfma_f32_16x16x32_bf16 v[112:115], v[152:155], v[156:159], v[112:115]
	ds_read_b128 v[156:159], v202 offset:4096
	global_load_lds_dwordx4 v200, s[50:51]
	s_waitcnt lgkmcnt(3)
	s_add_i32 m0, s41, 0x400
	s_add_u32 s52, s50, 0x4000
	s_addc_u32 s53, s51, 0
	v_mfma_f32_16x16x32_bf16 v[124:127], v[216:219], v[188:191], v[124:127]
	v_mfma_f32_16x16x32_bf16 v[120:123], v[220:223], v[188:191], v[120:123]
	v_mfma_f32_16x16x32_bf16 v[116:119], v[224:227], v[188:191], v[116:119]
	v_mfma_f32_16x16x32_bf16 v[112:115], v[228:231], v[188:191], v[112:115]
	ds_read_b128 v[188:191], v203 offset:4096
	global_load_lds_dwordx4 v201, s[52:53]
	s_waitcnt lgkmcnt(3)
	s_add_i32 m0, s41, 0x800
	s_add_u32 s52, s50, 0x8000
	s_addc_u32 s53, s51, 0
	v_mfma_f32_16x16x32_bf16 v[108:111], v[140:143], v[192:195], v[108:111]
	v_mfma_f32_16x16x32_bf16 v[104:107], v[144:147], v[192:195], v[104:107]
	v_mfma_f32_16x16x32_bf16 v[100:103], v[148:151], v[192:195], v[100:103]
	v_mfma_f32_16x16x32_bf16 v[96:99], v[152:155], v[192:195], v[96:99]
	ds_read_b128 v[192:195], v202 offset:6144
	global_load_lds_dwordx4 v200, s[52:53]
	s_waitcnt lgkmcnt(3)
	s_add_i32 m0, s41, 0xc00
	s_add_u32 s52, s50, 0xc000
	s_addc_u32 s53, s51, 0
	v_mfma_f32_16x16x32_bf16 v[108:111], v[216:219], v[208:211], v[108:111]
	v_mfma_f32_16x16x32_bf16 v[104:107], v[220:223], v[208:211], v[104:107]
	v_mfma_f32_16x16x32_bf16 v[100:103], v[224:227], v[208:211], v[100:103]
	v_mfma_f32_16x16x32_bf16 v[96:99], v[228:231], v[208:211], v[96:99]
	ds_read_b128 v[208:211], v203 offset:6144
	global_load_lds_dwordx4 v201, s[52:53]
	s_waitcnt lgkmcnt(3)
	v_mfma_f32_16x16x32_bf16 v[84:87], v[140:143], v[156:159], v[84:87]
	v_mfma_f32_16x16x32_bf16 v[72:75], v[144:147], v[156:159], v[72:75]
	v_mfma_f32_16x16x32_bf16 v[68:71], v[148:151], v[156:159], v[68:71]
	v_mfma_f32_16x16x32_bf16 v[64:67], v[152:155], v[156:159], v[64:67]
	s_waitcnt lgkmcnt(2)
	v_mfma_f32_16x16x32_bf16 v[84:87], v[216:219], v[188:191], v[84:87]
	v_mfma_f32_16x16x32_bf16 v[72:75], v[220:223], v[188:191], v[72:75]
	v_mfma_f32_16x16x32_bf16 v[68:71], v[224:227], v[188:191], v[68:71]
	v_mfma_f32_16x16x32_bf16 v[64:67], v[228:231], v[188:191], v[64:67]
	s_waitcnt lgkmcnt(1)
	v_mfma_f32_16x16x32_bf16 v[60:63], v[140:143], v[192:195], v[60:63]
	v_mfma_f32_16x16x32_bf16 v[56:59], v[144:147], v[192:195], v[56:59]
	v_mfma_f32_16x16x32_bf16 v[52:55], v[148:151], v[192:195], v[52:55]
	v_mfma_f32_16x16x32_bf16 v[48:51], v[152:155], v[192:195], v[48:51]
	s_waitcnt lgkmcnt(0)
	v_mfma_f32_16x16x32_bf16 v[60:63], v[216:219], v[208:211], v[60:63]
	v_mfma_f32_16x16x32_bf16 v[56:59], v[220:223], v[208:211], v[56:59]
	v_mfma_f32_16x16x32_bf16 v[52:55], v[224:227], v[208:211], v[52:55]
	v_mfma_f32_16x16x32_bf16 v[48:51], v[228:231], v[208:211], v[48:51]
	s_add_i32 s42, s13, 1
	s_cmp_lg_u32 s13, 2
	s_cselect_b32 s13, s42, 0
	s_mul_i32 s15, s13, 0x4000
	s_add_i32 s15, s15, 16
	s_add_i32 s41, s13, 2
	s_cmp_ge_u32 s41, 3
	s_cselect_b32 s42, 3, 0
	s_sub_i32 s41, s41, s42
	s_mul_i32 s41, s41, 0x4000
	s_add_i32 s41, s41, 16
	s_add_i32 s41, s41, s54
	s_add_u32 s50, s18, s32
	s_addc_u32 s51, s19, 0
	s_add_u32 s50, s50, 0x20000
	s_addc_u32 s51, s51, 0
	s_add_u32 s46, s28, s32
	s_addc_u32 s47, s29, 0
	s_waitcnt vmcnt(4)
	s_barrier
	v_add_u32_e32 v202, s15, v196
	v_add_u32_e32 v203, s15, v197
	ds_read_b128 v[156:159], v202
	ds_read_b128 v[188:191], v203
	ds_read_b128 v[192:195], v202 offset:2048
	ds_read_b128 v[208:211], v203 offset:2048
	s_waitcnt lgkmcnt(3)
	s_add_i32 m0, s54, 0xc010
	v_mfma_f32_16x16x32_bf16 v[44:47], v[140:143], v[156:159], v[44:47]
	v_mfma_f32_16x16x32_bf16 v[40:43], v[144:147], v[156:159], v[40:43]
	v_mfma_f32_16x16x32_bf16 v[36:39], v[148:151], v[156:159], v[36:39]
	v_mfma_f32_16x16x32_bf16 v[32:35], v[152:155], v[156:159], v[32:35]
	ds_read_b128 v[156:159], v202 offset:4096
	global_load_lds_dwordx4 v200, s[46:47]
	s_waitcnt lgkmcnt(3)
	s_add_i32 m0, s54, 0xc410
	s_add_u32 s52, s46, 0x4000
	s_addc_u32 s53, s47, 0
	v_mfma_f32_16x16x32_bf16 v[44:47], v[216:219], v[188:191], v[44:47]
	v_mfma_f32_16x16x32_bf16 v[40:43], v[220:223], v[188:191], v[40:43]
	v_mfma_f32_16x16x32_bf16 v[36:39], v[224:227], v[188:191], v[36:39]
	v_mfma_f32_16x16x32_bf16 v[32:35], v[228:231], v[188:191], v[32:35]
	ds_read_b128 v[188:191], v203 offset:4096
	global_load_lds_dwordx4 v201, s[52:53]
	s_waitcnt lgkmcnt(3)
	s_add_i32 m0, s54, 0xc810
	s_add_u32 s52, s46, 0x8000
	s_addc_u32 s53, s47, 0
	v_mfma_f32_16x16x32_bf16 v[28:31], v[140:143], v[192:195], v[28:31]
	v_mfma_f32_16x16x32_bf16 v[24:27], v[144:147], v[192:195], v[24:27]
	v_mfma_f32_16x16x32_bf16 v[20:23], v[148:151], v[192:195], v[20:23]
	v_mfma_f32_16x16x32_bf16 v[16:19], v[152:155], v[192:195], v[16:19]
	ds_read_b128 v[192:195], v202 offset:6144
	global_load_lds_dwordx4 v200, s[52:53]
	s_waitcnt lgkmcnt(3)
	s_add_i32 m0, s54, 0xcc10
	s_add_u32 s52, s46, 0xc000
	s_addc_u32 s53, s47, 0
	v_mfma_f32_16x16x32_bf16 v[28:31], v[216:219], v[208:211], v[28:31]
	v_mfma_f32_16x16x32_bf16 v[24:27], v[220:223], v[208:211], v[24:27]
	v_mfma_f32_16x16x32_bf16 v[20:23], v[224:227], v[208:211], v[20:23]
	v_mfma_f32_16x16x32_bf16 v[16:19], v[228:231], v[208:211], v[16:19]
	ds_read_b128 v[208:211], v203 offset:6144
	global_load_lds_dwordx4 v201, s[52:53]
	s_waitcnt lgkmcnt(3)
	s_add_i32 m0, s41, 0x0
	v_mfma_f32_16x16x32_bf16 v[12:15], v[140:143], v[156:159], v[12:15]
	v_mfma_f32_16x16x32_bf16 v[8:11], v[144:147], v[156:159], v[8:11]
	v_mfma_f32_16x16x32_bf16 v[4:7], v[148:151], v[156:159], v[4:7]
	v_mfma_f32_16x16x32_bf16 v[0:3], v[152:155], v[156:159], v[0:3]
	global_load_lds_dwordx4 v200, s[50:51]
	s_waitcnt lgkmcnt(2)
	s_add_i32 m0, s41, 0x400
	s_add_u32 s52, s50, 0x4000
	s_addc_u32 s53, s51, 0
	v_mfma_f32_16x16x32_bf16 v[12:15], v[216:219], v[188:191], v[12:15]
	v_mfma_f32_16x16x32_bf16 v[8:11], v[220:223], v[188:191], v[8:11]
	v_mfma_f32_16x16x32_bf16 v[4:7], v[224:227], v[188:191], v[4:7]
	v_mfma_f32_16x16x32_bf16 v[0:3], v[228:231], v[188:191], v[0:3]
	global_load_lds_dwordx4 v201, s[52:53]
	s_waitcnt lgkmcnt(1)
	s_add_i32 m0, s41, 0x800
	s_add_u32 s52, s50, 0x8000
	s_addc_u32 s53, s51, 0
	v_mfma_f32_16x16x32_bf16 v[76:79], v[140:143], v[192:195], v[76:79]
	v_mfma_f32_16x16x32_bf16 v[80:83], v[144:147], v[192:195], v[80:83]
	v_mfma_f32_16x16x32_bf16 v[88:91], v[148:151], v[192:195], v[88:91]
	v_mfma_f32_16x16x32_bf16 v[92:95], v[152:155], v[192:195], v[92:95]
	global_load_lds_dwordx4 v200, s[52:53]
	s_waitcnt lgkmcnt(0)
	s_add_i32 m0, s41, 0xc00
	s_add_u32 s52, s50, 0xc000
	s_addc_u32 s53, s51, 0
	v_mfma_f32_16x16x32_bf16 v[76:79], v[216:219], v[208:211], v[76:79]
	v_mfma_f32_16x16x32_bf16 v[80:83], v[220:223], v[208:211], v[80:83]
	v_mfma_f32_16x16x32_bf16 v[88:91], v[224:227], v[208:211], v[88:91]
	v_mfma_f32_16x16x32_bf16 v[92:95], v[228:231], v[208:211], v[92:95]
	global_load_lds_dwordx4 v201, s[52:53]
	s_add_i32 s42, s13, 1
	s_cmp_lg_u32 s13, 2
	s_cselect_b32 s13, s42, 0
	s_add_i32 s14, s14, 1
	s_cmp_eq_u32 s14, 16
	s_cbranch_scc0 .LBB1_56
	s_setprio 0
	s_cmpk_lt_i32 s7, 0x80
	v_readlane_b32 s10, v242, 5
	s_waitcnt vmcnt(0)
	s_cselect_b64 s[8:9], -1, 0
	v_readlane_b32 s11, v242, 6
	s_and_b64 s[8:9], s[10:11], s[8:9]
	s_mov_b64 s[42:43], -1
	s_and_b64 vcc, exec, s[8:9]
	v_cvt_pk_bf16_f32 v124, v124, v125
	v_cvt_pk_bf16_f32 v125, v126, v127
	v_cvt_pk_bf16_f32 v120, v120, v121
	v_cvt_pk_bf16_f32 v121, v122, v123
	v_cvt_pk_bf16_f32 v116, v116, v117
	v_cvt_pk_bf16_f32 v117, v118, v119
	v_cvt_pk_bf16_f32 v112, v112, v113
	v_cvt_pk_bf16_f32 v113, v114, v115
	v_cvt_pk_bf16_f32 v108, v108, v109
	v_cvt_pk_bf16_f32 v109, v110, v111
	v_cvt_pk_bf16_f32 v104, v104, v105
	v_cvt_pk_bf16_f32 v105, v106, v107
	v_cvt_pk_bf16_f32 v100, v100, v101
	v_cvt_pk_bf16_f32 v101, v102, v103
	v_cvt_pk_bf16_f32 v96, v96, v97
	v_cvt_pk_bf16_f32 v97, v98, v99
	v_cvt_pk_bf16_f32 v84, v84, v85
	v_cvt_pk_bf16_f32 v85, v86, v87
	v_cvt_pk_bf16_f32 v72, v72, v73
	v_cvt_pk_bf16_f32 v73, v74, v75
	v_cvt_pk_bf16_f32 v68, v68, v69
	v_cvt_pk_bf16_f32 v69, v70, v71
	v_cvt_pk_bf16_f32 v64, v64, v65
	v_cvt_pk_bf16_f32 v65, v66, v67
	v_cvt_pk_bf16_f32 v60, v60, v61
	v_cvt_pk_bf16_f32 v61, v62, v63
	v_cvt_pk_bf16_f32 v56, v56, v57
	v_cvt_pk_bf16_f32 v57, v58, v59
	v_cvt_pk_bf16_f32 v52, v52, v53
	v_cvt_pk_bf16_f32 v53, v54, v55
	v_cvt_pk_bf16_f32 v48, v48, v49
	v_cvt_pk_bf16_f32 v49, v50, v51
	v_cvt_pk_bf16_f32 v44, v44, v45
	v_cvt_pk_bf16_f32 v45, v46, v47
	v_cvt_pk_bf16_f32 v40, v40, v41
	v_cvt_pk_bf16_f32 v41, v42, v43
	v_cvt_pk_bf16_f32 v36, v36, v37
	v_cvt_pk_bf16_f32 v37, v38, v39
	v_cvt_pk_bf16_f32 v32, v32, v33
	v_cvt_pk_bf16_f32 v33, v34, v35
	v_cvt_pk_bf16_f32 v28, v28, v29
	v_cvt_pk_bf16_f32 v29, v30, v31
	v_cvt_pk_bf16_f32 v24, v24, v25
	v_cvt_pk_bf16_f32 v25, v26, v27
	v_cvt_pk_bf16_f32 v20, v20, v21
	v_cvt_pk_bf16_f32 v21, v22, v23
	v_cvt_pk_bf16_f32 v16, v16, v17
	v_cvt_pk_bf16_f32 v17, v18, v19
	v_cvt_pk_bf16_f32 v12, v12, v13
	v_cvt_pk_bf16_f32 v13, v14, v15
	v_cvt_pk_bf16_f32 v14, v8, v9
	v_cvt_pk_bf16_f32 v15, v10, v11
	v_cvt_pk_bf16_f32 v8, v4, v5
	v_cvt_pk_bf16_f32 v9, v6, v7
	v_cvt_pk_bf16_f32 v10, v0, v1
	v_cvt_pk_bf16_f32 v11, v2, v3
	v_cvt_pk_bf16_f32 v2, v76, v77
	v_cvt_pk_bf16_f32 v3, v78, v79
	v_cvt_pk_bf16_f32 v6, v80, v81
	v_cvt_pk_bf16_f32 v7, v82, v83
	v_cvt_pk_bf16_f32 v0, v88, v89
	v_cvt_pk_bf16_f32 v1, v90, v91
	v_cvt_pk_bf16_f32 v4, v92, v93
	v_cvt_pk_bf16_f32 v5, v94, v95
	s_waitcnt vmcnt(0)
	s_barrier
	s_cbranch_vccnz .LBB1_59
	s_load_dwordx16 s[64:79], s[0:1], 0x140
	v_or_b32_e32 v18, s4, v135
	v_add_u32_e32 v18, s6, v18
	v_lshl_or_b32 v19, v136, 2, s40
	v_or_b32_e32 v22, s5, v19
	v_ashrrev_i32_e32 v19, 31, v18
	v_lshlrev_b64 v[26:27], 12, v[18:19]
	v_ashrrev_i32_e32 v23, 31, v22
	s_waitcnt lgkmcnt(0)
	v_lshl_add_u64 v[26:27], s[76:77], 0, v[26:27]
	v_lshlrev_b64 v[22:23], 1, v[22:23]
	v_lshl_add_u64 v[26:27], v[26:27], 0, v[22:23]
	global_store_dwordx2 v[26:27], v[124:125], off
	global_store_dwordx2 v[26:27], v[120:121], off offset:32
	global_store_dwordx2 v[26:27], v[116:117], off offset:64
	global_store_dwordx2 v[26:27], v[112:113], off offset:96
	v_or_b32_e32 v26, 16, v18
	v_ashrrev_i32_e32 v27, 31, v26
	v_lshlrev_b64 v[26:27], 12, v[26:27]
	v_lshl_add_u64 v[26:27], s[76:77], 0, v[26:27]
	v_lshl_add_u64 v[26:27], v[26:27], 0, v[22:23]
	global_store_dwordx2 v[26:27], v[108:109], off
	global_store_dwordx2 v[26:27], v[104:105], off offset:32
	global_store_dwordx2 v[26:27], v[100:101], off offset:64
	global_store_dwordx2 v[26:27], v[96:97], off offset:96
	v_or_b32_e32 v26, 32, v18
	v_ashrrev_i32_e32 v27, 31, v26
	v_lshlrev_b64 v[26:27], 12, v[26:27]
	v_lshl_add_u64 v[26:27], s[76:77], 0, v[26:27]
	v_lshl_add_u64 v[26:27], v[26:27], 0, v[22:23]
	global_store_dwordx2 v[26:27], v[84:85], off
	global_store_dwordx2 v[26:27], v[72:73], off offset:32
	global_store_dwordx2 v[26:27], v[68:69], off offset:64
	global_store_dwordx2 v[26:27], v[64:65], off offset:96
	v_or_b32_e32 v26, 48, v18
	v_ashrrev_i32_e32 v27, 31, v26
	v_lshlrev_b64 v[26:27], 12, v[26:27]
	v_lshl_add_u64 v[26:27], s[76:77], 0, v[26:27]
	v_lshl_add_u64 v[26:27], v[26:27], 0, v[22:23]
	global_store_dwordx2 v[26:27], v[60:61], off
	global_store_dwordx2 v[26:27], v[56:57], off offset:32
	global_store_dwordx2 v[26:27], v[52:53], off offset:64
	global_store_dwordx2 v[26:27], v[48:49], off offset:96
	v_or_b32_e32 v26, 64, v18
	v_ashrrev_i32_e32 v27, 31, v26
	v_lshlrev_b64 v[26:27], 12, v[26:27]
	v_lshl_add_u64 v[26:27], s[76:77], 0, v[26:27]
	v_lshl_add_u64 v[26:27], v[26:27], 0, v[22:23]
	global_store_dwordx2 v[26:27], v[44:45], off
	global_store_dwordx2 v[26:27], v[40:41], off offset:32
	global_store_dwordx2 v[26:27], v[36:37], off offset:64
	global_store_dwordx2 v[26:27], v[32:33], off offset:96
	v_or_b32_e32 v26, 0x50, v18
	v_ashrrev_i32_e32 v27, 31, v26
	v_lshlrev_b64 v[26:27], 12, v[26:27]
	v_lshl_add_u64 v[26:27], s[76:77], 0, v[26:27]
	v_lshl_add_u64 v[26:27], v[26:27], 0, v[22:23]
	global_store_dwordx2 v[26:27], v[28:29], off
	global_store_dwordx2 v[26:27], v[24:25], off offset:32
	global_store_dwordx2 v[26:27], v[20:21], off offset:64
	global_store_dwordx2 v[26:27], v[16:17], off offset:96
	v_or_b32_e32 v26, 0x60, v18
	v_ashrrev_i32_e32 v27, 31, v26
	v_lshlrev_b64 v[26:27], 12, v[26:27]
	v_lshl_add_u64 v[26:27], s[76:77], 0, v[26:27]
	v_or_b32_e32 v18, 0x70, v18
	v_lshl_add_u64 v[26:27], v[26:27], 0, v[22:23]
	v_ashrrev_i32_e32 v19, 31, v18
	global_store_dwordx2 v[26:27], v[12:13], off
	global_store_dwordx2 v[26:27], v[14:15], off offset:32
	global_store_dwordx2 v[26:27], v[8:9], off offset:64
	global_store_dwordx2 v[26:27], v[10:11], off offset:96
	v_lshlrev_b64 v[18:19], 12, v[18:19]
	v_lshl_add_u64 v[18:19], s[76:77], 0, v[18:19]
	s_load_dwordx16 s[64:79], s[0:1], 0x100
	v_lshl_add_u64 v[18:19], v[18:19], 0, v[22:23]
	s_mov_b64 s[42:43], 0
	global_store_dwordx2 v[18:19], v[2:3], off
	global_store_dwordx2 v[18:19], v[6:7], off offset:32
	global_store_dwordx2 v[18:19], v[0:1], off offset:64
	global_store_dwordx2 v[18:19], v[4:5], off offset:96

.Lg96pf_skip_LBB1_82:
	s_mov_b32 s59, 0
	s_mov_b32 s18, 0
	s_waitcnt vmcnt(0)
	s_barrier
	v_readlane_b32 s19, v242, 0
	v_readlane_b32 s13, v241, 24
	s_nop 3
	s_lshr_b32 s13, s13, 3
	s_cmp_ge_u32 s19, s13
	s_cbranch_scc0 .Lprio_done_LBB1_82
	s_setprio 1
.Lprio_done_LBB1_82:
.LBB1_82:
	s_lshl_b32 s19, s18, 8
	s_add_i32 s19, s19, 0x80
	s_min_u32 s19, s19, 0x780
	s_add_u32 s40, s8, s19
	s_addc_u32 s41, s9, 0
	s_add_u32 s42, s10, s19
	s_addc_u32 s43, s11, 0
	ds_read_b128 v[142:145], v234 offset:0
	ds_read_b128 v[146:149], v234 offset:2048
	ds_read_b128 v[150:153], v234 offset:4096
	ds_read_b128 v[154:157], v234 offset:6144
	ds_read_b128 v[130:133], v232 offset:0
	ds_read_b128 v[134:137], v232 offset:2048
	ds_read_b128 v[138:141], v232 offset:4096
	ds_read_b128 v[216:219], v235 offset:0
	ds_read_b128 v[220:223], v235 offset:2048
	ds_read_b128 v[224:227], v235 offset:4096
	ds_read_b128 v[228:231], v235 offset:6144
	ds_read_b128 v[188:191], v233 offset:0
	ds_read_b128 v[192:195], v233 offset:2048
	ds_read_b128 v[196:199], v233 offset:4096
	s_waitcnt lgkmcnt(9)
	s_add_i32 m0, s16, 0x7010
	s_nop 0
	v_mfma_f32_16x16x32_bf16 v[72:75], v[142:145], v[130:133], v[72:75]
	global_load_lds_dwordx4 v238, s[40:41]
	s_add_i32 m0, s16, 0x7410
	s_add_u32 s12, s40, 0x4000
	s_addc_u32 s13, s41, 0
	v_mfma_f32_16x16x32_bf16 v[68:71], v[146:149], v[130:133], v[68:71]
	global_load_lds_dwordx4 v239, s[12:13]
	v_mfma_f32_16x16x32_bf16 v[44:47], v[150:153], v[130:133], v[44:47]
	v_mfma_f32_16x16x32_bf16 v[32:35], v[154:157], v[130:133], v[32:35]
	s_waitcnt lgkmcnt(8)
	s_add_i32 m0, s16, 0x7810
	s_add_u32 s12, s40, 0x8000
	s_addc_u32 s13, s41, 0
	v_mfma_f32_16x16x32_bf16 v[28:31], v[142:145], v[134:137], v[28:31]
	v_mfma_f32_16x16x32_bf16 v[24:27], v[146:149], v[134:137], v[24:27]
	global_load_lds_dwordx4 v238, s[12:13]
	v_mfma_f32_16x16x32_bf16 v[20:23], v[150:153], v[134:137], v[20:23]
	v_mfma_f32_16x16x32_bf16 v[16:19], v[154:157], v[134:137], v[16:19]
	s_waitcnt lgkmcnt(7)
	s_add_i32 m0, s17, 0xa010
	s_nop 0
	v_mfma_f32_16x16x32_bf16 v[12:15], v[142:145], v[138:141], v[12:15]
	v_mfma_f32_16x16x32_bf16 v[8:11], v[146:149], v[138:141], v[8:11]
	global_load_lds_dwordx4 v236, s[42:43]
	v_mfma_f32_16x16x32_bf16 v[4:7], v[150:153], v[138:141], v[4:7]
	v_mfma_f32_16x16x32_bf16 v[0:3], v[154:157], v[138:141], v[0:3]
	s_waitcnt lgkmcnt(2)
	s_add_i32 m0, s17, 0xa410
	s_add_u32 s12, s42, 0x4000
	s_addc_u32 s13, s43, 0
	v_mfma_f32_16x16x32_bf16 v[72:75], v[216:219], v[188:191], v[72:75]
	v_mfma_f32_16x16x32_bf16 v[68:71], v[220:223], v[188:191], v[68:71]
	global_load_lds_dwordx4 v237, s[12:13]
	v_mfma_f32_16x16x32_bf16 v[44:47], v[224:227], v[188:191], v[44:47]
	v_mfma_f32_16x16x32_bf16 v[32:35], v[228:231], v[188:191], v[32:35]
	s_waitcnt lgkmcnt(1)
	s_add_i32 m0, s17, 0xa810
	s_add_u32 s12, s42, 0x8000
	s_addc_u32 s13, s43, 0
	v_mfma_f32_16x16x32_bf16 v[28:31], v[216:219], v[192:195], v[28:31]
	v_mfma_f32_16x16x32_bf16 v[24:27], v[220:223], v[192:195], v[24:27]
	global_load_lds_dwordx4 v236, s[12:13]
	v_mfma_f32_16x16x32_bf16 v[20:23], v[224:227], v[192:195], v[20:23]
	v_mfma_f32_16x16x32_bf16 v[16:19], v[228:231], v[192:195], v[16:19]
	s_waitcnt lgkmcnt(0)
	s_add_i32 m0, s17, 0xac10
	s_add_u32 s12, s42, 0xc000
	s_addc_u32 s13, s43, 0
	v_mfma_f32_16x16x32_bf16 v[12:15], v[216:219], v[196:199], v[12:15]
	v_mfma_f32_16x16x32_bf16 v[8:11], v[220:223], v[196:199], v[8:11]
	global_load_lds_dwordx4 v237, s[12:13]
	v_mfma_f32_16x16x32_bf16 v[4:7], v[224:227], v[196:199], v[4:7]
	v_mfma_f32_16x16x32_bf16 v[0:3], v[228:231], v[196:199], v[0:3]
	s_waitcnt vmcnt(0)
	s_barrier
	s_lshl_b32 s19, s18, 8
	s_add_i32 s19, s19, 0x100
	s_min_u32 s19, s19, 0x780
	s_add_u32 s40, s8, s19
	s_addc_u32 s41, s9, 0
	s_add_u32 s42, s10, s19
	s_addc_u32 s43, s11, 0
	ds_read_b128 v[142:145], v234 offset:28672
	ds_read_b128 v[146:149], v234 offset:30720
	ds_read_b128 v[150:153], v234 offset:32768
	ds_read_b128 v[154:157], v234 offset:34816
	ds_read_b128 v[130:133], v232 offset:28672
	ds_read_b128 v[134:137], v232 offset:30720
	ds_read_b128 v[138:141], v232 offset:32768
	ds_read_b128 v[216:219], v235 offset:28672
	ds_read_b128 v[220:223], v235 offset:30720
	ds_read_b128 v[224:227], v235 offset:32768
	ds_read_b128 v[228:231], v235 offset:34816
	ds_read_b128 v[188:191], v233 offset:28672
	ds_read_b128 v[192:195], v233 offset:30720
	ds_read_b128 v[196:199], v233 offset:32768
	s_waitcnt lgkmcnt(9)
	s_add_i32 m0, s16, 0x10
	s_nop 0
	v_mfma_f32_16x16x32_bf16 v[72:75], v[142:145], v[130:133], v[72:75]
	global_load_lds_dwordx4 v238, s[40:41]
	s_add_i32 m0, s16, 0x410
	s_add_u32 s12, s40, 0x4000
	s_addc_u32 s13, s41, 0
	v_mfma_f32_16x16x32_bf16 v[68:71], v[146:149], v[130:133], v[68:71]
	global_load_lds_dwordx4 v239, s[12:13]
	v_mfma_f32_16x16x32_bf16 v[44:47], v[150:153], v[130:133], v[44:47]
	v_mfma_f32_16x16x32_bf16 v[32:35], v[154:157], v[130:133], v[32:35]
	s_waitcnt lgkmcnt(8)
	s_add_i32 m0, s16, 0x810
	s_add_u32 s12, s40, 0x8000
	s_addc_u32 s13, s41, 0
	v_mfma_f32_16x16x32_bf16 v[28:31], v[142:145], v[134:137], v[28:31]
	v_mfma_f32_16x16x32_bf16 v[24:27], v[146:149], v[134:137], v[24:27]
	global_load_lds_dwordx4 v238, s[12:13]
	v_mfma_f32_16x16x32_bf16 v[20:23], v[150:153], v[134:137], v[20:23]
	v_mfma_f32_16x16x32_bf16 v[16:19], v[154:157], v[134:137], v[16:19]
	s_waitcnt lgkmcnt(7)
	s_add_i32 m0, s17, 0x3010
	s_nop 0
	v_mfma_f32_16x16x32_bf16 v[12:15], v[142:145], v[138:141], v[12:15]
	v_mfma_f32_16x16x32_bf16 v[8:11], v[146:149], v[138:141], v[8:11]
	global_load_lds_dwordx4 v236, s[42:43]
	v_mfma_f32_16x16x32_bf16 v[4:7], v[150:153], v[138:141], v[4:7]
	v_mfma_f32_16x16x32_bf16 v[0:3], v[154:157], v[138:141], v[0:3]
	s_waitcnt lgkmcnt(2)
	s_add_i32 m0, s17, 0x3410
	s_add_u32 s12, s42, 0x4000
	s_addc_u32 s13, s43, 0
	v_mfma_f32_16x16x32_bf16 v[72:75], v[216:219], v[188:191], v[72:75]
	v_mfma_f32_16x16x32_bf16 v[68:71], v[220:223], v[188:191], v[68:71]
	global_load_lds_dwordx4 v237, s[12:13]
	v_mfma_f32_16x16x32_bf16 v[44:47], v[224:227], v[188:191], v[44:47]
	v_mfma_f32_16x16x32_bf16 v[32:35], v[228:231], v[188:191], v[32:35]
	s_waitcnt lgkmcnt(1)
	s_add_i32 m0, s17, 0x3810
	s_add_u32 s12, s42, 0x8000
	s_addc_u32 s13, s43, 0
	v_mfma_f32_16x16x32_bf16 v[28:31], v[216:219], v[192:195], v[28:31]
	v_mfma_f32_16x16x32_bf16 v[24:27], v[220:223], v[192:195], v[24:27]
	global_load_lds_dwordx4 v236, s[12:13]
	v_mfma_f32_16x16x32_bf16 v[20:23], v[224:227], v[192:195], v[20:23]
	v_mfma_f32_16x16x32_bf16 v[16:19], v[228:231], v[192:195], v[16:19]
	s_waitcnt lgkmcnt(0)
	s_add_i32 m0, s17, 0x3c10
	s_add_u32 s12, s42, 0xc000
	s_addc_u32 s13, s43, 0
	v_mfma_f32_16x16x32_bf16 v[12:15], v[216:219], v[196:199], v[12:15]
	v_mfma_f32_16x16x32_bf16 v[8:11], v[220:223], v[196:199], v[8:11]
	global_load_lds_dwordx4 v237, s[12:13]
	v_mfma_f32_16x16x32_bf16 v[4:7], v[224:227], v[196:199], v[4:7]
	v_mfma_f32_16x16x32_bf16 v[0:3], v[228:231], v[196:199], v[0:3]
	s_waitcnt vmcnt(0)
	s_barrier
	s_add_i32 s18, s18, 1
	s_cmp_eq_u32 s18, 8
	s_cbranch_scc0 .LBB1_82
	s_setprio 0
	s_waitcnt vmcnt(0)
	v_readlane_b32 s14, v242, 0
	s_add_i32 s15, s2, 1
	s_lshl_b32 s15, s15, 3
	s_and_b32 s24, s14, 7
	s_or_b32 s15, s15, s24
	s_mul_i32 s15, s15, s55
	s_lshr_b32 s14, s14, 3
	s_add_i32 s15, s15, s14
	s_cmp_lt_u32 s15, 0x580
	s_cselect_b32 s59, 1, 0
	s_cbranch_scc0 .Lg96pf_none_g3
	s_lshr_b32 s14, s15, 6
	s_lshl_b32 s14, s14, 3
	s_and_b32 s24, s15, 7
	s_add_i32 s14, s14, s24
	s_mul_i32 s14, s14, 96
	s_sub_i32 s14, s14, s5
	s_bfe_u32 s24, s15, 0x30003
	s_lshl_b32 s24, s24, 7
	s_sub_i32 s24, s24, s4
	s_ashr_i32 s15, s14, 31
	s_lshl_b64 s[14:15], s[14:15], 11
	s_add_u32 s88, s8, s14
	s_addc_u32 s89, s9, s15
	s_ashr_i32 s25, s24, 31
	s_lshl_b64 s[24:25], s[24:25], 11
	s_add_u32 s90, s10, s24
	s_addc_u32 s91, s11, s25
	s_add_i32 m0, s16, 0x10
	s_nop 0
	global_load_lds_dwordx4 v238, s[88:89]
	s_add_i32 m0, s16, 0x410
	s_add_u32 s14, s88, 0x4000
	s_addc_u32 s15, s89, 0
	global_load_lds_dwordx4 v239, s[14:15]
	s_add_i32 m0, s16, 0x810
	s_add_u32 s14, s88, 0x8000
	s_addc_u32 s15, s89, 0
	global_load_lds_dwordx4 v238, s[14:15]
	s_add_i32 m0, s17, 0x3010
	s_nop 0
	global_load_lds_dwordx4 v236, s[90:91]
	s_add_i32 m0, s17, 0x3410
	s_add_u32 s14, s90, 0x4000
	s_addc_u32 s15, s91, 0
	global_load_lds_dwordx4 v237, s[14:15]
	s_add_i32 m0, s17, 0x3810
	s_add_u32 s14, s90, 0x8000
	s_addc_u32 s15, s91, 0
	global_load_lds_dwordx4 v236, s[14:15]
	s_add_i32 m0, s17, 0x3c10
	s_add_u32 s14, s90, 0xc000
	s_addc_u32 s15, s91, 0
	global_load_lds_dwordx4 v237, s[14:15]

.Lprio_done_LBB1_90:
.LBB1_90:
	s_lshl_b32 s19, s18, 8
	s_add_i32 s19, s19, 0x80
	s_min_u32 s19, s19, 0x780
	s_add_u32 s40, s8, s19
	s_addc_u32 s41, s9, 0
	s_add_u32 s42, s10, s19
	s_addc_u32 s43, s11, 0
	ds_read_b128 v[142:145], v234 offset:0
	ds_read_b128 v[146:149], v234 offset:2048
	ds_read_b128 v[150:153], v234 offset:4096
	ds_read_b128 v[154:157], v234 offset:6144
	ds_read_b128 v[130:133], v232 offset:0
	ds_read_b128 v[134:137], v232 offset:2048
	ds_read_b128 v[138:141], v232 offset:4096
	ds_read_b128 v[216:219], v235 offset:0
	ds_read_b128 v[220:223], v235 offset:2048
	ds_read_b128 v[224:227], v235 offset:4096
	ds_read_b128 v[228:231], v235 offset:6144
	ds_read_b128 v[188:191], v233 offset:0
	ds_read_b128 v[192:195], v233 offset:2048
	ds_read_b128 v[196:199], v233 offset:4096
	s_waitcnt lgkmcnt(9)
	s_add_i32 m0, s16, 0x7010
	s_nop 0
	v_mfma_f32_16x16x32_bf16 v[72:75], v[142:145], v[130:133], v[72:75]
	global_load_lds_dwordx4 v238, s[40:41]
	s_add_i32 m0, s16, 0x7410
	s_add_u32 s12, s40, 0x4000
	s_addc_u32 s13, s41, 0
	v_mfma_f32_16x16x32_bf16 v[40:43], v[146:149], v[130:133], v[40:43]
	global_load_lds_dwordx4 v239, s[12:13]
	v_mfma_f32_16x16x32_bf16 v[36:39], v[150:153], v[130:133], v[36:39]
	v_mfma_f32_16x16x32_bf16 v[32:35], v[154:157], v[130:133], v[32:35]
	s_waitcnt lgkmcnt(8)
	s_add_i32 m0, s16, 0x7810
	s_add_u32 s12, s40, 0x8000
	s_addc_u32 s13, s41, 0
	v_mfma_f32_16x16x32_bf16 v[28:31], v[142:145], v[134:137], v[28:31]
	v_mfma_f32_16x16x32_bf16 v[24:27], v[146:149], v[134:137], v[24:27]
	global_load_lds_dwordx4 v238, s[12:13]
	v_mfma_f32_16x16x32_bf16 v[20:23], v[150:153], v[134:137], v[20:23]
	v_mfma_f32_16x16x32_bf16 v[16:19], v[154:157], v[134:137], v[16:19]
	s_waitcnt lgkmcnt(7)
	s_add_i32 m0, s17, 0xa010
	s_nop 0
	v_mfma_f32_16x16x32_bf16 v[12:15], v[142:145], v[138:141], v[12:15]
	v_mfma_f32_16x16x32_bf16 v[8:11], v[146:149], v[138:141], v[8:11]
	global_load_lds_dwordx4 v236, s[42:43]
	v_mfma_f32_16x16x32_bf16 v[4:7], v[150:153], v[138:141], v[4:7]
	v_mfma_f32_16x16x32_bf16 v[0:3], v[154:157], v[138:141], v[0:3]
	s_waitcnt lgkmcnt(2)
	s_add_i32 m0, s17, 0xa410
	s_add_u32 s12, s42, 0x4000
	s_addc_u32 s13, s43, 0
	v_mfma_f32_16x16x32_bf16 v[72:75], v[216:219], v[188:191], v[72:75]
	v_mfma_f32_16x16x32_bf16 v[40:43], v[220:223], v[188:191], v[40:43]
	global_load_lds_dwordx4 v237, s[12:13]
	v_mfma_f32_16x16x32_bf16 v[36:39], v[224:227], v[188:191], v[36:39]
	v_mfma_f32_16x16x32_bf16 v[32:35], v[228:231], v[188:191], v[32:35]
	s_waitcnt lgkmcnt(1)
	s_add_i32 m0, s17, 0xa810
	s_add_u32 s12, s42, 0x8000
	s_addc_u32 s13, s43, 0
	v_mfma_f32_16x16x32_bf16 v[28:31], v[216:219], v[192:195], v[28:31]
	v_mfma_f32_16x16x32_bf16 v[24:27], v[220:223], v[192:195], v[24:27]
	global_load_lds_dwordx4 v236, s[12:13]
	v_mfma_f32_16x16x32_bf16 v[20:23], v[224:227], v[192:195], v[20:23]
	v_mfma_f32_16x16x32_bf16 v[16:19], v[228:231], v[192:195], v[16:19]
	s_waitcnt lgkmcnt(0)
	s_add_i32 m0, s17, 0xac10
	s_add_u32 s12, s42, 0xc000
	s_addc_u32 s13, s43, 0
	v_mfma_f32_16x16x32_bf16 v[12:15], v[216:219], v[196:199], v[12:15]
	v_mfma_f32_16x16x32_bf16 v[8:11], v[220:223], v[196:199], v[8:11]
	global_load_lds_dwordx4 v237, s[12:13]
	v_mfma_f32_16x16x32_bf16 v[4:7], v[224:227], v[196:199], v[4:7]
	v_mfma_f32_16x16x32_bf16 v[0:3], v[228:231], v[196:199], v[0:3]
	s_waitcnt vmcnt(0)
	s_barrier
	s_lshl_b32 s19, s18, 8
	s_add_i32 s19, s19, 0x100
	s_min_u32 s19, s19, 0x780
	s_add_u32 s40, s8, s19
	s_addc_u32 s41, s9, 0
	s_add_u32 s42, s10, s19
	s_addc_u32 s43, s11, 0
	ds_read_b128 v[142:145], v234 offset:28672
	ds_read_b128 v[146:149], v234 offset:30720
	ds_read_b128 v[150:153], v234 offset:32768
	ds_read_b128 v[154:157], v234 offset:34816
	ds_read_b128 v[130:133], v232 offset:28672
	ds_read_b128 v[134:137], v232 offset:30720
	ds_read_b128 v[138:141], v232 offset:32768
	ds_read_b128 v[216:219], v235 offset:28672
	ds_read_b128 v[220:223], v235 offset:30720
	ds_read_b128 v[224:227], v235 offset:32768
	ds_read_b128 v[228:231], v235 offset:34816
	ds_read_b128 v[188:191], v233 offset:28672
	ds_read_b128 v[192:195], v233 offset:30720
	ds_read_b128 v[196:199], v233 offset:32768
	s_waitcnt lgkmcnt(9)
	s_add_i32 m0, s16, 0x10
	s_nop 0
	v_mfma_f32_16x16x32_bf16 v[72:75], v[142:145], v[130:133], v[72:75]
	global_load_lds_dwordx4 v238, s[40:41]
	s_add_i32 m0, s16, 0x410
	s_add_u32 s12, s40, 0x4000
	s_addc_u32 s13, s41, 0
	v_mfma_f32_16x16x32_bf16 v[40:43], v[146:149], v[130:133], v[40:43]
	global_load_lds_dwordx4 v239, s[12:13]
	v_mfma_f32_16x16x32_bf16 v[36:39], v[150:153], v[130:133], v[36:39]
	v_mfma_f32_16x16x32_bf16 v[32:35], v[154:157], v[130:133], v[32:35]
	s_waitcnt lgkmcnt(8)
	s_add_i32 m0, s16, 0x810
	s_add_u32 s12, s40, 0x8000
	s_addc_u32 s13, s41, 0
	v_mfma_f32_16x16x32_bf16 v[28:31], v[142:145], v[134:137], v[28:31]
	v_mfma_f32_16x16x32_bf16 v[24:27], v[146:149], v[134:137], v[24:27]
	global_load_lds_dwordx4 v238, s[12:13]
	v_mfma_f32_16x16x32_bf16 v[20:23], v[150:153], v[134:137], v[20:23]
	v_mfma_f32_16x16x32_bf16 v[16:19], v[154:157], v[134:137], v[16:19]
	s_waitcnt lgkmcnt(7)
	s_add_i32 m0, s17, 0x3010
	s_nop 0
	v_mfma_f32_16x16x32_bf16 v[12:15], v[142:145], v[138:141], v[12:15]
	v_mfma_f32_16x16x32_bf16 v[8:11], v[146:149], v[138:141], v[8:11]
	global_load_lds_dwordx4 v236, s[42:43]
	v_mfma_f32_16x16x32_bf16 v[4:7], v[150:153], v[138:141], v[4:7]
	v_mfma_f32_16x16x32_bf16 v[0:3], v[154:157], v[138:141], v[0:3]
	s_waitcnt lgkmcnt(2)
	s_add_i32 m0, s17, 0x3410
	s_add_u32 s12, s42, 0x4000
	s_addc_u32 s13, s43, 0
	v_mfma_f32_16x16x32_bf16 v[72:75], v[216:219], v[188:191], v[72:75]
	v_mfma_f32_16x16x32_bf16 v[40:43], v[220:223], v[188:191], v[40:43]
	global_load_lds_dwordx4 v237, s[12:13]
	v_mfma_f32_16x16x32_bf16 v[36:39], v[224:227], v[188:191], v[36:39]
	v_mfma_f32_16x16x32_bf16 v[32:35], v[228:231], v[188:191], v[32:35]
	s_waitcnt lgkmcnt(1)
	s_add_i32 m0, s17, 0x3810
	s_add_u32 s12, s42, 0x8000
	s_addc_u32 s13, s43, 0
	v_mfma_f32_16x16x32_bf16 v[28:31], v[216:219], v[192:195], v[28:31]
	v_mfma_f32_16x16x32_bf16 v[24:27], v[220:223], v[192:195], v[24:27]
	global_load_lds_dwordx4 v236, s[12:13]
	v_mfma_f32_16x16x32_bf16 v[20:23], v[224:227], v[192:195], v[20:23]
	v_mfma_f32_16x16x32_bf16 v[16:19], v[228:231], v[192:195], v[16:19]
	s_waitcnt lgkmcnt(0)
	s_add_i32 m0, s17, 0x3c10
	s_add_u32 s12, s42, 0xc000
	s_addc_u32 s13, s43, 0
	v_mfma_f32_16x16x32_bf16 v[12:15], v[216:219], v[196:199], v[12:15]
	v_mfma_f32_16x16x32_bf16 v[8:11], v[220:223], v[196:199], v[8:11]
	global_load_lds_dwordx4 v237, s[12:13]
	v_mfma_f32_16x16x32_bf16 v[4:7], v[224:227], v[196:199], v[4:7]
	v_mfma_f32_16x16x32_bf16 v[0:3], v[228:231], v[196:199], v[0:3]
	s_waitcnt vmcnt(0)
	s_barrier
	s_add_i32 s18, s18, 1
	s_cmp_eq_u32 s18, 8
	s_cbranch_scc0 .LBB1_90
	s_setprio 0
	s_waitcnt vmcnt(0)
	v_readlane_b32 s14, v242, 0
	s_add_i32 s15, s2, 1
	s_lshl_b32 s15, s15, 3
	s_and_b32 s24, s14, 7
	s_or_b32 s15, s15, s24
	s_mul_i32 s15, s15, s55
	s_lshr_b32 s14, s14, 3
	s_add_i32 s15, s15, s14
	s_cmp_lt_u32 s15, 0x580
	s_cselect_b32 s59, 1, 0
	s_cbranch_scc0 .Lg96pf_none_g2a
	s_lshr_b32 s14, s15, 6
	s_lshl_b32 s14, s14, 3
	s_and_b32 s24, s15, 7
	s_add_i32 s14, s14, s24
	s_mul_i32 s14, s14, 96
	s_sub_i32 s14, s14, s5
	s_bfe_u32 s24, s15, 0x30003
	s_lshl_b32 s24, s24, 7
	s_sub_i32 s24, s24, s4
	s_ashr_i32 s15, s14, 31
	s_lshl_b64 s[14:15], s[14:15], 11
	s_add_u32 s88, s8, s14
	s_addc_u32 s89, s9, s15
	s_ashr_i32 s25, s24, 31
	s_lshl_b64 s[24:25], s[24:25], 11
	s_add_u32 s90, s10, s24
	s_addc_u32 s91, s11, s25
	s_add_i32 m0, s16, 0x10
	s_nop 0
	global_load_lds_dwordx4 v238, s[88:89]
	s_add_i32 m0, s16, 0x410
	s_add_u32 s14, s88, 0x4000
	s_addc_u32 s15, s89, 0
	global_load_lds_dwordx4 v239, s[14:15]
	s_add_i32 m0, s16, 0x810
	s_add_u32 s14, s88, 0x8000
	s_addc_u32 s15, s89, 0
	global_load_lds_dwordx4 v238, s[14:15]
	s_add_i32 m0, s17, 0x3010
	s_nop 0
	global_load_lds_dwordx4 v236, s[90:91]
	s_add_i32 m0, s17, 0x3410
	s_add_u32 s14, s90, 0x4000
	s_addc_u32 s15, s91, 0
	global_load_lds_dwordx4 v237, s[14:15]
	s_add_i32 m0, s17, 0x3810
	s_add_u32 s14, s90, 0x8000
	s_addc_u32 s15, s91, 0
	global_load_lds_dwordx4 v236, s[14:15]
	s_add_i32 m0, s17, 0x3c10
	s_add_u32 s14, s90, 0xc000
	s_addc_u32 s15, s91, 0
	global_load_lds_dwordx4 v237, s[14:15]

.Lprio_done_LBB1_808:
.LBB1_808:
	s_lshl_b32 s19, s18, 8
	s_add_i32 s19, s19, 0x80
	s_min_u32 s19, s19, 0x780
	s_add_u32 s40, s8, s19
	s_addc_u32 s41, s9, 0
	s_add_u32 s42, s10, s19
	s_addc_u32 s43, s11, 0
	ds_read_b128 v[142:145], v234 offset:0
	ds_read_b128 v[146:149], v234 offset:2048
	ds_read_b128 v[150:153], v234 offset:4096
	ds_read_b128 v[154:157], v234 offset:6144
	ds_read_b128 v[130:133], v232 offset:0
	ds_read_b128 v[134:137], v232 offset:2048
	ds_read_b128 v[138:141], v232 offset:4096
	ds_read_b128 v[216:219], v235 offset:0
	ds_read_b128 v[220:223], v235 offset:2048
	ds_read_b128 v[224:227], v235 offset:4096
	ds_read_b128 v[228:231], v235 offset:6144
	ds_read_b128 v[188:191], v233 offset:0
	ds_read_b128 v[192:195], v233 offset:2048
	ds_read_b128 v[196:199], v233 offset:4096
	s_waitcnt lgkmcnt(9)
	s_add_i32 m0, s16, 0x7010
	s_nop 0
	v_mfma_f32_16x16x32_bf16 v[72:75], v[142:145], v[130:133], v[72:75]
	global_load_lds_dwordx4 v238, s[40:41]
	s_add_i32 m0, s16, 0x7410
	s_add_u32 s12, s40, 0x4000
	s_addc_u32 s13, s41, 0
	v_mfma_f32_16x16x32_bf16 v[40:43], v[146:149], v[130:133], v[40:43]
	global_load_lds_dwordx4 v239, s[12:13]
	v_mfma_f32_16x16x32_bf16 v[36:39], v[150:153], v[130:133], v[36:39]
	v_mfma_f32_16x16x32_bf16 v[32:35], v[154:157], v[130:133], v[32:35]
	s_waitcnt lgkmcnt(8)
	s_add_i32 m0, s16, 0x7810
	s_add_u32 s12, s40, 0x8000
	s_addc_u32 s13, s41, 0
	v_mfma_f32_16x16x32_bf16 v[28:31], v[142:145], v[134:137], v[28:31]
	v_mfma_f32_16x16x32_bf16 v[24:27], v[146:149], v[134:137], v[24:27]
	global_load_lds_dwordx4 v238, s[12:13]
	v_mfma_f32_16x16x32_bf16 v[20:23], v[150:153], v[134:137], v[20:23]
	v_mfma_f32_16x16x32_bf16 v[16:19], v[154:157], v[134:137], v[16:19]
	s_waitcnt lgkmcnt(7)
	s_add_i32 m0, s17, 0xa010
	s_nop 0
	v_mfma_f32_16x16x32_bf16 v[12:15], v[142:145], v[138:141], v[12:15]
	v_mfma_f32_16x16x32_bf16 v[8:11], v[146:149], v[138:141], v[8:11]
	global_load_lds_dwordx4 v236, s[42:43]
	v_mfma_f32_16x16x32_bf16 v[4:7], v[150:153], v[138:141], v[4:7]
	v_mfma_f32_16x16x32_bf16 v[0:3], v[154:157], v[138:141], v[0:3]
	s_waitcnt lgkmcnt(2)
	s_add_i32 m0, s17, 0xa410
	s_add_u32 s12, s42, 0x4000
	s_addc_u32 s13, s43, 0
	v_mfma_f32_16x16x32_bf16 v[72:75], v[216:219], v[188:191], v[72:75]
	v_mfma_f32_16x16x32_bf16 v[40:43], v[220:223], v[188:191], v[40:43]
	global_load_lds_dwordx4 v237, s[12:13]
	v_mfma_f32_16x16x32_bf16 v[36:39], v[224:227], v[188:191], v[36:39]
	v_mfma_f32_16x16x32_bf16 v[32:35], v[228:231], v[188:191], v[32:35]
	s_waitcnt lgkmcnt(1)
	s_add_i32 m0, s17, 0xa810
	s_add_u32 s12, s42, 0x8000
	s_addc_u32 s13, s43, 0
	v_mfma_f32_16x16x32_bf16 v[28:31], v[216:219], v[192:195], v[28:31]
	v_mfma_f32_16x16x32_bf16 v[24:27], v[220:223], v[192:195], v[24:27]
	global_load_lds_dwordx4 v236, s[12:13]
	v_mfma_f32_16x16x32_bf16 v[20:23], v[224:227], v[192:195], v[20:23]
	v_mfma_f32_16x16x32_bf16 v[16:19], v[228:231], v[192:195], v[16:19]
	s_waitcnt lgkmcnt(0)
	s_add_i32 m0, s17, 0xac10
	s_add_u32 s12, s42, 0xc000
	s_addc_u32 s13, s43, 0
	v_mfma_f32_16x16x32_bf16 v[12:15], v[216:219], v[196:199], v[12:15]
	v_mfma_f32_16x16x32_bf16 v[8:11], v[220:223], v[196:199], v[8:11]
	global_load_lds_dwordx4 v237, s[12:13]
	v_mfma_f32_16x16x32_bf16 v[4:7], v[224:227], v[196:199], v[4:7]
	v_mfma_f32_16x16x32_bf16 v[0:3], v[228:231], v[196:199], v[0:3]
	s_waitcnt vmcnt(0)
	s_barrier
	s_lshl_b32 s19, s18, 8
	s_add_i32 s19, s19, 0x100
	s_min_u32 s19, s19, 0x780
	s_add_u32 s40, s8, s19
	s_addc_u32 s41, s9, 0
	s_add_u32 s42, s10, s19
	s_addc_u32 s43, s11, 0
	ds_read_b128 v[142:145], v234 offset:28672
	ds_read_b128 v[146:149], v234 offset:30720
	ds_read_b128 v[150:153], v234 offset:32768
	ds_read_b128 v[154:157], v234 offset:34816
	ds_read_b128 v[130:133], v232 offset:28672
	ds_read_b128 v[134:137], v232 offset:30720
	ds_read_b128 v[138:141], v232 offset:32768
	ds_read_b128 v[216:219], v235 offset:28672
	ds_read_b128 v[220:223], v235 offset:30720
	ds_read_b128 v[224:227], v235 offset:32768
	ds_read_b128 v[228:231], v235 offset:34816
	ds_read_b128 v[188:191], v233 offset:28672
	ds_read_b128 v[192:195], v233 offset:30720
	ds_read_b128 v[196:199], v233 offset:32768
	s_waitcnt lgkmcnt(9)
	s_add_i32 m0, s16, 0x10
	s_nop 0
	v_mfma_f32_16x16x32_bf16 v[72:75], v[142:145], v[130:133], v[72:75]
	global_load_lds_dwordx4 v238, s[40:41]
	s_add_i32 m0, s16, 0x410
	s_add_u32 s12, s40, 0x4000
	s_addc_u32 s13, s41, 0
	v_mfma_f32_16x16x32_bf16 v[40:43], v[146:149], v[130:133], v[40:43]
	global_load_lds_dwordx4 v239, s[12:13]
	v_mfma_f32_16x16x32_bf16 v[36:39], v[150:153], v[130:133], v[36:39]
	v_mfma_f32_16x16x32_bf16 v[32:35], v[154:157], v[130:133], v[32:35]
	s_waitcnt lgkmcnt(8)
	s_add_i32 m0, s16, 0x810
	s_add_u32 s12, s40, 0x8000
	s_addc_u32 s13, s41, 0
	v_mfma_f32_16x16x32_bf16 v[28:31], v[142:145], v[134:137], v[28:31]
	v_mfma_f32_16x16x32_bf16 v[24:27], v[146:149], v[134:137], v[24:27]
	global_load_lds_dwordx4 v238, s[12:13]
	v_mfma_f32_16x16x32_bf16 v[20:23], v[150:153], v[134:137], v[20:23]
	v_mfma_f32_16x16x32_bf16 v[16:19], v[154:157], v[134:137], v[16:19]
	s_waitcnt lgkmcnt(7)
	s_add_i32 m0, s17, 0x3010
	s_nop 0
	v_mfma_f32_16x16x32_bf16 v[12:15], v[142:145], v[138:141], v[12:15]
	v_mfma_f32_16x16x32_bf16 v[8:11], v[146:149], v[138:141], v[8:11]
	global_load_lds_dwordx4 v236, s[42:43]
	v_mfma_f32_16x16x32_bf16 v[4:7], v[150:153], v[138:141], v[4:7]
	v_mfma_f32_16x16x32_bf16 v[0:3], v[154:157], v[138:141], v[0:3]
	s_waitcnt lgkmcnt(2)
	s_add_i32 m0, s17, 0x3410
	s_add_u32 s12, s42, 0x4000
	s_addc_u32 s13, s43, 0
	v_mfma_f32_16x16x32_bf16 v[72:75], v[216:219], v[188:191], v[72:75]
	v_mfma_f32_16x16x32_bf16 v[40:43], v[220:223], v[188:191], v[40:43]
	global_load_lds_dwordx4 v237, s[12:13]
	v_mfma_f32_16x16x32_bf16 v[36:39], v[224:227], v[188:191], v[36:39]
	v_mfma_f32_16x16x32_bf16 v[32:35], v[228:231], v[188:191], v[32:35]
	s_waitcnt lgkmcnt(1)
	s_add_i32 m0, s17, 0x3810
	s_add_u32 s12, s42, 0x8000
	s_addc_u32 s13, s43, 0
	v_mfma_f32_16x16x32_bf16 v[28:31], v[216:219], v[192:195], v[28:31]
	v_mfma_f32_16x16x32_bf16 v[24:27], v[220:223], v[192:195], v[24:27]
	global_load_lds_dwordx4 v236, s[12:13]
	v_mfma_f32_16x16x32_bf16 v[20:23], v[224:227], v[192:195], v[20:23]
	v_mfma_f32_16x16x32_bf16 v[16:19], v[228:231], v[192:195], v[16:19]
	s_waitcnt lgkmcnt(0)
	s_add_i32 m0, s17, 0x3c10
	s_add_u32 s12, s42, 0xc000
	s_addc_u32 s13, s43, 0
	v_mfma_f32_16x16x32_bf16 v[12:15], v[216:219], v[196:199], v[12:15]
	v_mfma_f32_16x16x32_bf16 v[8:11], v[220:223], v[196:199], v[8:11]
	global_load_lds_dwordx4 v237, s[12:13]
	v_mfma_f32_16x16x32_bf16 v[4:7], v[224:227], v[196:199], v[4:7]
	v_mfma_f32_16x16x32_bf16 v[0:3], v[228:231], v[196:199], v[0:3]
	s_waitcnt vmcnt(0)
	s_barrier
	s_add_i32 s18, s18, 1
	s_cmp_eq_u32 s18, 8
	s_cbranch_scc0 .LBB1_808
	s_setprio 0
	s_waitcnt vmcnt(0)
	v_readlane_b32 s30, v242, 63
	s_nop 1
	s_add_i32 s31, s2, s30
	s_cmp_lt_u32 s31, 0x580
	s_cselect_b32 s59, 1, 0
	s_cbranch_scc0 .Lg96pf_none_g2b
	s_mul_i32 s38, s31, 745
	s_lshr_b32 s38, s38, 17
	s_mul_i32 s39, s38, 176
	s_sub_i32 s39, s31, s39
	s_mul_i32 s30, s39, 96
	s_sub_i32 s30, s30, s5
	s_ashr_i32 s31, s30, 31
	s_lshl_b64 s[30:31], s[30:31], 11
	s_add_u32 s88, s8, s30
	s_addc_u32 s89, s9, s31
	s_lshl_b32 s24, s38, 7
	s_sub_i32 s24, s24, s4
	s_ashr_i32 s25, s24, 31
	s_lshl_b64 s[24:25], s[24:25], 11
	s_add_u32 s90, s10, s24
	s_addc_u32 s91, s11, s25
	s_add_i32 m0, s16, 0x10
	s_nop 0
	global_load_lds_dwordx4 v238, s[88:89]
	s_add_i32 m0, s16, 0x410
	s_add_u32 s30, s88, 0x4000
	s_addc_u32 s31, s89, 0
	global_load_lds_dwordx4 v239, s[30:31]
	s_add_i32 m0, s16, 0x810
	s_add_u32 s30, s88, 0x8000
	s_addc_u32 s31, s89, 0
	global_load_lds_dwordx4 v238, s[30:31]
	s_add_i32 m0, s17, 0x3010
	s_nop 0
	global_load_lds_dwordx4 v236, s[90:91]
	s_add_i32 m0, s17, 0x3410
	s_add_u32 s30, s90, 0x4000
	s_addc_u32 s31, s91, 0
	global_load_lds_dwordx4 v237, s[30:31]
	s_add_i32 m0, s17, 0x3810
	s_add_u32 s30, s90, 0x8000
	s_addc_u32 s31, s91, 0
	global_load_lds_dwordx4 v236, s[30:31]
	s_add_i32 m0, s17, 0x3c10
	s_add_u32 s30, s90, 0xc000
	s_addc_u32 s31, s91, 0
	global_load_lds_dwordx4 v237, s[30:31]

.LBB1_1179:
	v_mov_b32_e32 v138, v162
	s_lshl_b32 s6, s5, 8
	v_readfirstlane_b32 s7, v138
	v_lshrrev_b32_e32 v0, 3, v138
	v_and_b32_e32 v0, 6, v0
	s_movk_i32 s11, 0x78
	s_and_b32 s9, s7, 0xffffffc0
	s_waitcnt lgkmcnt(0)
	v_bfe_u32 v2, v138, 2, 4
	v_lshrrev_b32_e64 v0, v0, s11
	s_add_i32 s9, s9, s6
	v_xor_b32_e32 v3, v0, v138
	v_or_b32_e32 v0, s9, v2
	v_ashrrev_i32_e32 v1, 31, v0
	v_lshlrev_b64 v[0:1], 11, v[0:1]
	v_lshlrev_b32_e32 v3, 4, v3
	s_lshl_b32 s30, s4, 7
	v_lshl_add_u64 v[0:1], s[74:75], 0, v[0:1]
	v_and_b32_e32 v128, 48, v3
	s_load_dwordx16 s[80:95], s[0:1], 0xc0
	s_ashr_i32 s8, s7, 6
	v_lshl_add_u64 v[130:131], v[0:1], 0, v[128:129]
	v_or_b32_e32 v0, s30, v2
	v_lshl_add_u32 v0, s8, 5, v0
	v_ashrrev_i32_e32 v1, 31, v0
	v_lshlrev_b64 v[0:1], 11, v[0:1]
	s_waitcnt lgkmcnt(0)
	v_lshl_add_u64 v[0:1], s[84:85], 0, v[0:1]
	v_lshl_add_u64 v[132:133], v[0:1], 0, v[128:129]
	v_lshrrev_b32_e32 v0, 1, v138
	v_and_b32_e32 v0, 6, v0
	v_bfe_u32 v140, v138, 4, 2
	s_lshl_b32 s9, s8, 12
	v_lshrrev_b32_e64 v0, v0, s11
	v_and_b32_e32 v139, 15, v138
	s_lshl_b32 s10, s8, 11
	s_and_b32 s8, s7, 0xffffff80
	v_bitop3_b32 v0, v0, v140, 3 bitop3:0x6c
	s_and_b32 s7, s7, 64
	s_add_i32 s11, s9, 16
	v_lshlrev_b32_e32 v134, 4, v0
	v_or_b32_e32 v0, s7, v139
	s_mov_b32 m0, s11
	v_lshlrev_b32_e32 v135, 6, v0
	s_barrier
	v_lshl_add_u64 v[0:1], v[130:131], 0, s[34:35]
	s_add_i32 m0, s11, 0x400
	s_mov_b64 s[12:13], 0x10000
	v_lshl_add_u64 v[0:1], v[130:131], 0, s[12:13]
	s_add_i32 m0, s11, 0x800
	s_mov_b64 s[12:13], 0x18000
	v_lshl_add_u64 v[0:1], v[130:131], 0, s[12:13]
	s_add_i32 m0, s11, 0xc00
	s_sub_i32 s12, s11, s10
	s_add_i32 m0, s12, 0x4000
	v_lshl_add_u64 v[0:1], v[132:133], 0, s[34:35]
	s_add_i32 m0, s12, 0x4400
	s_mov_b64 s[14:15], 0x8040
	v_lshl_add_u64 v[0:1], v[130:131], 0, 64
	s_add_i32 m0, s11, 0x6000
	s_mov_b64 s[16:17], 0x10040
	v_lshl_add_u64 v[0:1], v[130:131], 0, s[14:15]
	s_add_i32 m0, s11, 0x6400
	v_or_b32_e32 v141, s8, v139
	v_lshl_add_u64 v[0:1], v[130:131], 0, s[16:17]
	s_add_i32 m0, s11, 0x6800
	s_mov_b64 s[16:17], 0x18040
	v_lshl_add_u64 v[0:1], v[130:131], 0, s[16:17]
	s_add_i32 m0, s11, 0x6c00
	v_lshlrev_b32_e32 v128, 6, v141
	v_lshl_add_u64 v[0:1], v[132:133], 0, 64
	s_add_i32 m0, s12, 0xa000
	s_mov_b32 s11, 0
	v_lshl_add_u64 v[0:1], v[132:133], 0, s[14:15]
	s_add_i32 m0, s12, 0xa400
	s_mov_b32 s12, 0
	v_mov_b32_e32 v0, 0
	v_mov_b32_e32 v1, v0
	v_mov_b32_e32 v2, v0
	v_mov_b32_e32 v3, v0
	v_mov_b32_e32 v4, v0
	v_mov_b32_e32 v5, v0
	v_mov_b32_e32 v6, v0
	v_mov_b32_e32 v7, v0
	v_mov_b32_e32 v8, v0
	v_mov_b32_e32 v9, v0
	v_mov_b32_e32 v10, v0
	v_mov_b32_e32 v11, v0
	v_mov_b32_e32 v12, v0
	v_mov_b32_e32 v13, v0
	v_mov_b32_e32 v14, v0
	v_mov_b32_e32 v15, v0
	v_mov_b32_e32 v16, v0
	v_mov_b32_e32 v17, v0
	v_mov_b32_e32 v18, v0
	v_mov_b32_e32 v19, v0
	v_mov_b32_e32 v20, v0
	v_mov_b32_e32 v21, v0
	v_mov_b32_e32 v22, v0
	v_mov_b32_e32 v23, v0
	v_mov_b32_e32 v24, v0
	v_mov_b32_e32 v25, v0
	v_mov_b32_e32 v26, v0
	v_mov_b32_e32 v27, v0
	v_mov_b32_e32 v28, v0
	v_mov_b32_e32 v29, v0
	v_mov_b32_e32 v30, v0
	v_mov_b32_e32 v31, v0
	v_mov_b32_e32 v32, v0
	v_mov_b32_e32 v33, v0
	v_mov_b32_e32 v34, v0
	v_mov_b32_e32 v35, v0
	v_mov_b32_e32 v36, v0
	v_mov_b32_e32 v37, v0
	v_mov_b32_e32 v38, v0
	v_mov_b32_e32 v39, v0
	v_mov_b32_e32 v40, v0
	v_mov_b32_e32 v41, v0
	v_mov_b32_e32 v42, v0
	v_mov_b32_e32 v43, v0
	v_mov_b32_e32 v44, v0
	v_mov_b32_e32 v45, v0
	v_mov_b32_e32 v46, v0
	v_mov_b32_e32 v47, v0
	v_mov_b32_e32 v48, v0
	v_mov_b32_e32 v49, v0
	v_mov_b32_e32 v50, v0
	v_mov_b32_e32 v51, v0
	v_mov_b32_e32 v68, v0
	v_mov_b32_e32 v69, v0
	v_mov_b32_e32 v70, v0
	v_mov_b32_e32 v71, v0
	v_mov_b32_e32 v72, v0
	v_mov_b32_e32 v73, v0
	v_mov_b32_e32 v74, v0
	v_mov_b32_e32 v75, v0
	v_mov_b32_e32 v76, v0
	v_mov_b32_e32 v77, v0
	v_mov_b32_e32 v78, v0
	v_mov_b32_e32 v79, v0
	v_mov_b32_e32 v80, v0
	v_mov_b32_e32 v81, v0
	v_mov_b32_e32 v82, v0
	v_mov_b32_e32 v83, v0
	v_mov_b32_e32 v84, v0
	v_mov_b32_e32 v85, v0
	v_mov_b32_e32 v86, v0
	v_mov_b32_e32 v87, v0
	v_mov_b32_e32 v88, v0
	v_mov_b32_e32 v89, v0
	v_mov_b32_e32 v90, v0
	v_mov_b32_e32 v91, v0
	v_mov_b32_e32 v92, v0
	v_mov_b32_e32 v93, v0
	v_mov_b32_e32 v94, v0
	v_mov_b32_e32 v95, v0
	v_mov_b32_e32 v96, v0
	v_mov_b32_e32 v97, v0
	v_mov_b32_e32 v98, v0
	v_mov_b32_e32 v99, v0
	v_mov_b32_e32 v100, v0
	v_mov_b32_e32 v101, v0
	v_mov_b32_e32 v102, v0
	v_mov_b32_e32 v103, v0
	v_mov_b32_e32 v104, v0
	v_mov_b32_e32 v105, v0
	v_mov_b32_e32 v106, v0
	v_mov_b32_e32 v107, v0
	v_mov_b32_e32 v108, v0
	v_mov_b32_e32 v109, v0
	v_mov_b32_e32 v110, v0
	v_mov_b32_e32 v111, v0
	v_mov_b32_e32 v112, v0
	v_mov_b32_e32 v113, v0
	v_mov_b32_e32 v114, v0
	v_mov_b32_e32 v115, v0
	v_mov_b32_e32 v116, v0
	v_mov_b32_e32 v117, v0
	v_mov_b32_e32 v118, v0
	v_mov_b32_e32 v119, v0
	v_mov_b32_e32 v120, v0
	v_mov_b32_e32 v121, v0
	v_mov_b32_e32 v122, v0
	v_mov_b32_e32 v123, v0
	v_mov_b32_e32 v124, v0
	v_mov_b32_e32 v125, v0
	v_mov_b32_e32 v126, v0
	v_mov_b32_e32 v127, v0
	v_mov_b32_e32 v60, v0
	v_mov_b32_e32 v61, v0
	v_mov_b32_e32 v62, v0
	v_mov_b32_e32 v63, v0
	v_mov_b32_e32 v64, v0
	v_mov_b32_e32 v65, v0
	v_mov_b32_e32 v66, v0
	v_mov_b32_e32 v67, v0
	v_mov_b32_e32 v52, v0
	v_mov_b32_e32 v53, v0
	v_mov_b32_e32 v54, v0
	v_mov_b32_e32 v55, v0
	v_mov_b32_e32 v56, v0
	v_mov_b32_e32 v57, v0
	v_mov_b32_e32 v58, v0
	v_mov_b32_e32 v59, v0
	s_mov_b64 s[16:17], 0x10080
	v_and_b32_e32 v204, 15, v168
	v_lshrrev_b32_e32 v205, 4, v168
	v_bfe_u32 v206, v168, 1, 3
	v_xor_b32_e32 v205, v205, v206
	v_lshlrev_b32_e32 v205, 4, v205
	v_readfirstlane_b32 s15, v162
	v_readfirstlane_b32 s18, v130
	v_readfirstlane_b32 s19, v131
	v_readfirstlane_b32 s28, v132
	v_readfirstlane_b32 s29, v133
	s_lshr_b32 s15, s15, 6
	s_lshl_b32 s54, s15, 12
	s_lshr_b32 s41, s15, 1
	s_and_b32 s42, s15, 1
	v_lshl_add_u32 v206, s41, 6, v204
	v_lshl_add_u32 v196, v206, 7, v205
	v_xor_b32_e32 v197, 64, v196
	v_lshl_add_u32 v206, s42, 6, v204
	v_lshl_add_u32 v198, v206, 7, v205
	v_xor_b32_e32 v199, 64, v198
	v_add_u32_e32 v198, 0xc010, v198
	v_add_u32_e32 v199, 0xc010, v199
	v_lshrrev_b32_e32 v206, 3, v168
	v_and_b32_e32 v207, 7, v168
	v_lshrrev_b32_e32 v204, 1, v206
	v_xor_b32_e32 v207, v207, v204
	v_lshlrev_b32_e32 v207, 4, v207
	v_lshl_add_u32 v200, v206, 11, v207
	v_xor_b32_e32 v201, 64, v200
	s_lshl_b32 s42, s42, 16
	s_sub_u32 s18, s18, s42
	s_subb_u32 s19, s19, 0
	s_add_i32 s41, s54, 16
	s_add_i32 m0, s41, 0x0
	s_nop 0
	global_load_lds_dwordx4 v200, s[18:19]
	s_add_i32 m0, s41, 0x400
	s_add_u32 s52, s18, 0x4000
	s_addc_u32 s53, s19, 0
	global_load_lds_dwordx4 v201, s[52:53]
	s_add_i32 m0, s41, 0x800
	s_add_u32 s52, s18, 0x8000
	s_addc_u32 s53, s19, 0
	global_load_lds_dwordx4 v200, s[52:53]
	s_add_i32 m0, s41, 0xc00
	s_add_u32 s52, s18, 0xc000
	s_addc_u32 s53, s19, 0
	global_load_lds_dwordx4 v201, s[52:53]
	s_add_i32 m0, s54, 0xc010
	s_nop 0
	global_load_lds_dwordx4 v200, s[28:29]
	s_add_i32 m0, s54, 0xc410
	s_add_u32 s52, s28, 0x4000
	s_addc_u32 s53, s29, 0
	global_load_lds_dwordx4 v201, s[52:53]
	s_add_i32 m0, s54, 0xc810
	s_add_u32 s52, s28, 0x8000
	s_addc_u32 s53, s29, 0
	global_load_lds_dwordx4 v200, s[52:53]
	s_add_i32 m0, s54, 0xcc10
	s_add_u32 s52, s28, 0xc000
	s_addc_u32 s53, s29, 0
	global_load_lds_dwordx4 v201, s[52:53]
	s_add_u32 s50, s18, 0x20000
	s_addc_u32 s51, s19, 0
	s_add_i32 m0, s41, 0x4000
	s_nop 0
	global_load_lds_dwordx4 v200, s[50:51]
	s_add_i32 m0, s41, 0x4400
	s_add_u32 s52, s50, 0x4000
	s_addc_u32 s53, s51, 0
	global_load_lds_dwordx4 v201, s[52:53]
	s_add_i32 m0, s41, 0x4800
	s_add_u32 s52, s50, 0x8000
	s_addc_u32 s53, s51, 0
	global_load_lds_dwordx4 v200, s[52:53]
	s_add_i32 m0, s41, 0x4c00
	s_add_u32 s52, s50, 0xc000
	s_addc_u32 s53, s51, 0
	global_load_lds_dwordx4 v201, s[52:53]
	s_mov_b32 s13, 0
	s_mov_b32 s14, 0
	v_readlane_b32 s15, v242, 0
	v_readlane_b32 s41, v241, 24
	s_nop 3
	s_lshr_b32 s41, s41, 3
	s_cmp_ge_u32 s15, s41
	s_cbranch_scc0 .Lprio_done_LBB1_1180
	s_setprio 1
.Lprio_done_LBB1_1180:
.LBB1_1180:
	s_mul_i32 s15, s13, 0x4000
	s_add_i32 s15, s15, 16
	s_add_i32 s41, s13, 2
	s_cmp_ge_u32 s41, 3
	s_cselect_b32 s42, 3, 0
	s_sub_i32 s41, s41, s42
	s_mul_i32 s41, s41, 0x4000
	s_add_i32 s41, s41, 16
	s_add_i32 s41, s41, s54
	s_add_i32 s32, s14, 1
	s_min_u32 s32, s32, 15
	s_lshl_b32 s32, s32, 7
	s_add_u32 s50, s18, s32
	s_addc_u32 s51, s19, 0
	s_waitcnt vmcnt(4)
	s_barrier
	v_add_u32_e32 v202, s15, v196
	v_add_u32_e32 v203, s15, v197
	ds_read_b128 v[142:145], v198 offset:0
	ds_read_b128 v[146:149], v198 offset:2048
	ds_read_b128 v[150:153], v198 offset:4096
	ds_read_b128 v[154:157], v198 offset:6144
	ds_read_b128 v[158:161], v202
	ds_read_b128 v[216:219], v199 offset:0
	ds_read_b128 v[220:223], v199 offset:2048
	ds_read_b128 v[224:227], v199 offset:4096
	ds_read_b128 v[228:231], v199 offset:6144
	ds_read_b128 v[188:191], v203
	ds_read_b128 v[192:195], v202 offset:2048
	ds_read_b128 v[208:211], v203 offset:2048
	s_waitcnt lgkmcnt(7)
	s_add_i32 m0, s41, 0x0
	v_mfma_f32_16x16x32_bf16 v[124:127], v[142:145], v[158:161], v[124:127]
	v_mfma_f32_16x16x32_bf16 v[120:123], v[146:149], v[158:161], v[120:123]
	v_mfma_f32_16x16x32_bf16 v[116:119], v[150:153], v[158:161], v[116:119]
	v_mfma_f32_16x16x32_bf16 v[112:115], v[154:157], v[158:161], v[112:115]
	ds_read_b128 v[158:161], v202 offset:4096
	global_load_lds_dwordx4 v200, s[50:51]
	s_waitcnt lgkmcnt(3)
	s_add_i32 m0, s41, 0x400
	s_add_u32 s52, s50, 0x4000
	s_addc_u32 s53, s51, 0
	v_mfma_f32_16x16x32_bf16 v[124:127], v[216:219], v[188:191], v[124:127]
	v_mfma_f32_16x16x32_bf16 v[120:123], v[220:223], v[188:191], v[120:123]
	v_mfma_f32_16x16x32_bf16 v[116:119], v[224:227], v[188:191], v[116:119]
	v_mfma_f32_16x16x32_bf16 v[112:115], v[228:231], v[188:191], v[112:115]
	ds_read_b128 v[188:191], v203 offset:4096
	global_load_lds_dwordx4 v201, s[52:53]
	s_waitcnt lgkmcnt(3)
	s_add_i32 m0, s41, 0x800
	s_add_u32 s52, s50, 0x8000
	s_addc_u32 s53, s51, 0
	v_mfma_f32_16x16x32_bf16 v[108:111], v[142:145], v[192:195], v[108:111]
	v_mfma_f32_16x16x32_bf16 v[104:107], v[146:149], v[192:195], v[104:107]
	v_mfma_f32_16x16x32_bf16 v[100:103], v[150:153], v[192:195], v[100:103]
	v_mfma_f32_16x16x32_bf16 v[96:99], v[154:157], v[192:195], v[96:99]
	ds_read_b128 v[192:195], v202 offset:6144
	global_load_lds_dwordx4 v200, s[52:53]
	s_waitcnt lgkmcnt(3)
	s_add_i32 m0, s41, 0xc00
	s_add_u32 s52, s50, 0xc000
	s_addc_u32 s53, s51, 0
	v_mfma_f32_16x16x32_bf16 v[108:111], v[216:219], v[208:211], v[108:111]
	v_mfma_f32_16x16x32_bf16 v[104:107], v[220:223], v[208:211], v[104:107]
	v_mfma_f32_16x16x32_bf16 v[100:103], v[224:227], v[208:211], v[100:103]
	v_mfma_f32_16x16x32_bf16 v[96:99], v[228:231], v[208:211], v[96:99]
	ds_read_b128 v[208:211], v203 offset:6144
	global_load_lds_dwordx4 v201, s[52:53]
	s_waitcnt lgkmcnt(3)
	v_mfma_f32_16x16x32_bf16 v[92:95], v[142:145], v[158:161], v[92:95]
	v_mfma_f32_16x16x32_bf16 v[88:91], v[146:149], v[158:161], v[88:91]
	v_mfma_f32_16x16x32_bf16 v[84:87], v[150:153], v[158:161], v[84:87]
	v_mfma_f32_16x16x32_bf16 v[80:83], v[154:157], v[158:161], v[80:83]
	s_waitcnt lgkmcnt(2)
	v_mfma_f32_16x16x32_bf16 v[92:95], v[216:219], v[188:191], v[92:95]
	v_mfma_f32_16x16x32_bf16 v[88:91], v[220:223], v[188:191], v[88:91]
	v_mfma_f32_16x16x32_bf16 v[84:87], v[224:227], v[188:191], v[84:87]
	v_mfma_f32_16x16x32_bf16 v[80:83], v[228:231], v[188:191], v[80:83]
	s_waitcnt lgkmcnt(1)
	v_mfma_f32_16x16x32_bf16 v[76:79], v[142:145], v[192:195], v[76:79]
	v_mfma_f32_16x16x32_bf16 v[72:75], v[146:149], v[192:195], v[72:75]
	v_mfma_f32_16x16x32_bf16 v[68:71], v[150:153], v[192:195], v[68:71]
	v_mfma_f32_16x16x32_bf16 v[48:51], v[154:157], v[192:195], v[48:51]
	s_waitcnt lgkmcnt(0)
	v_mfma_f32_16x16x32_bf16 v[76:79], v[216:219], v[208:211], v[76:79]
	v_mfma_f32_16x16x32_bf16 v[72:75], v[220:223], v[208:211], v[72:75]
	v_mfma_f32_16x16x32_bf16 v[68:71], v[224:227], v[208:211], v[68:71]
	v_mfma_f32_16x16x32_bf16 v[48:51], v[228:231], v[208:211], v[48:51]
	s_add_i32 s42, s13, 1
	s_cmp_lg_u32 s13, 2
	s_cselect_b32 s13, s42, 0
	s_mul_i32 s15, s13, 0x4000
	s_add_i32 s15, s15, 16
	s_add_i32 s41, s13, 2
	s_cmp_ge_u32 s41, 3
	s_cselect_b32 s42, 3, 0
	s_sub_i32 s41, s41, s42
	s_mul_i32 s41, s41, 0x4000
	s_add_i32 s41, s41, 16
	s_add_i32 s41, s41, s54
	s_add_u32 s50, s18, s32
	s_addc_u32 s51, s19, 0
	s_add_u32 s50, s50, 0x20000
	s_addc_u32 s51, s51, 0
	s_add_u32 s46, s28, s32
	s_addc_u32 s47, s29, 0
	s_waitcnt vmcnt(4)
	s_barrier
	v_add_u32_e32 v202, s15, v196
	v_add_u32_e32 v203, s15, v197
	ds_read_b128 v[158:161], v202
	ds_read_b128 v[188:191], v203
	ds_read_b128 v[192:195], v202 offset:2048
	ds_read_b128 v[208:211], v203 offset:2048
	s_waitcnt lgkmcnt(3)
	s_add_i32 m0, s54, 0xc010
	v_mfma_f32_16x16x32_bf16 v[44:47], v[142:145], v[158:161], v[44:47]
	v_mfma_f32_16x16x32_bf16 v[40:43], v[146:149], v[158:161], v[40:43]
	v_mfma_f32_16x16x32_bf16 v[36:39], v[150:153], v[158:161], v[36:39]
	v_mfma_f32_16x16x32_bf16 v[32:35], v[154:157], v[158:161], v[32:35]
	ds_read_b128 v[158:161], v202 offset:4096
	global_load_lds_dwordx4 v200, s[46:47]
	s_waitcnt lgkmcnt(3)
	s_add_i32 m0, s54, 0xc410
	s_add_u32 s52, s46, 0x4000
	s_addc_u32 s53, s47, 0
	v_mfma_f32_16x16x32_bf16 v[44:47], v[216:219], v[188:191], v[44:47]
	v_mfma_f32_16x16x32_bf16 v[40:43], v[220:223], v[188:191], v[40:43]
	v_mfma_f32_16x16x32_bf16 v[36:39], v[224:227], v[188:191], v[36:39]
	v_mfma_f32_16x16x32_bf16 v[32:35], v[228:231], v[188:191], v[32:35]
	ds_read_b128 v[188:191], v203 offset:4096
	global_load_lds_dwordx4 v201, s[52:53]
	s_waitcnt lgkmcnt(3)
	s_add_i32 m0, s54, 0xc810
	s_add_u32 s52, s46, 0x8000
	s_addc_u32 s53, s47, 0
	v_mfma_f32_16x16x32_bf16 v[28:31], v[142:145], v[192:195], v[28:31]
	v_mfma_f32_16x16x32_bf16 v[24:27], v[146:149], v[192:195], v[24:27]
	v_mfma_f32_16x16x32_bf16 v[20:23], v[150:153], v[192:195], v[20:23]
	v_mfma_f32_16x16x32_bf16 v[16:19], v[154:157], v[192:195], v[16:19]
	ds_read_b128 v[192:195], v202 offset:6144
	global_load_lds_dwordx4 v200, s[52:53]
	s_waitcnt lgkmcnt(3)
	s_add_i32 m0, s54, 0xcc10
	s_add_u32 s52, s46, 0xc000
	s_addc_u32 s53, s47, 0
	v_mfma_f32_16x16x32_bf16 v[28:31], v[216:219], v[208:211], v[28:31]
	v_mfma_f32_16x16x32_bf16 v[24:27], v[220:223], v[208:211], v[24:27]
	v_mfma_f32_16x16x32_bf16 v[20:23], v[224:227], v[208:211], v[20:23]
	v_mfma_f32_16x16x32_bf16 v[16:19], v[228:231], v[208:211], v[16:19]
	ds_read_b128 v[208:211], v203 offset:6144
	global_load_lds_dwordx4 v201, s[52:53]
	s_waitcnt lgkmcnt(3)
	s_add_i32 m0, s41, 0x0
	v_mfma_f32_16x16x32_bf16 v[12:15], v[142:145], v[158:161], v[12:15]
	v_mfma_f32_16x16x32_bf16 v[8:11], v[146:149], v[158:161], v[8:11]
	v_mfma_f32_16x16x32_bf16 v[4:7], v[150:153], v[158:161], v[4:7]
	v_mfma_f32_16x16x32_bf16 v[0:3], v[154:157], v[158:161], v[0:3]
	global_load_lds_dwordx4 v200, s[50:51]
	s_waitcnt lgkmcnt(2)
	s_add_i32 m0, s41, 0x400
	s_add_u32 s52, s50, 0x4000
	s_addc_u32 s53, s51, 0
	v_mfma_f32_16x16x32_bf16 v[12:15], v[216:219], v[188:191], v[12:15]
	v_mfma_f32_16x16x32_bf16 v[8:11], v[220:223], v[188:191], v[8:11]
	v_mfma_f32_16x16x32_bf16 v[4:7], v[224:227], v[188:191], v[4:7]
	v_mfma_f32_16x16x32_bf16 v[0:3], v[228:231], v[188:191], v[0:3]
	global_load_lds_dwordx4 v201, s[52:53]
	s_waitcnt lgkmcnt(1)
	s_add_i32 m0, s41, 0x800
	s_add_u32 s52, s50, 0x8000
	s_addc_u32 s53, s51, 0
	v_mfma_f32_16x16x32_bf16 v[60:63], v[142:145], v[192:195], v[60:63]
	v_mfma_f32_16x16x32_bf16 v[64:67], v[146:149], v[192:195], v[64:67]
	v_mfma_f32_16x16x32_bf16 v[52:55], v[150:153], v[192:195], v[52:55]
	v_mfma_f32_16x16x32_bf16 v[56:59], v[154:157], v[192:195], v[56:59]
	global_load_lds_dwordx4 v200, s[52:53]
	s_waitcnt lgkmcnt(0)
	s_add_i32 m0, s41, 0xc00
	s_add_u32 s52, s50, 0xc000
	s_addc_u32 s53, s51, 0
	v_mfma_f32_16x16x32_bf16 v[60:63], v[216:219], v[208:211], v[60:63]
	v_mfma_f32_16x16x32_bf16 v[64:67], v[220:223], v[208:211], v[64:67]
	v_mfma_f32_16x16x32_bf16 v[52:55], v[224:227], v[208:211], v[52:55]
	v_mfma_f32_16x16x32_bf16 v[56:59], v[228:231], v[208:211], v[56:59]
	global_load_lds_dwordx4 v201, s[52:53]
	s_add_i32 s42, s13, 1
	s_cmp_lg_u32 s13, 2
	s_cselect_b32 s13, s42, 0
	s_add_i32 s14, s14, 1
	s_cmp_eq_u32 s14, 16
	s_cbranch_scc0 .LBB1_1180
	s_setprio 0
	s_waitcnt vmcnt(0)
	s_waitcnt vmcnt(0)
	s_barrier
	s_load_dwordx8 s[80:87], s[0:1], 0x180
	s_cmp_lt_i32 s4, 64
	v_readlane_b32 s12, v242, 9
	s_cselect_b64 s[10:11], -1, 0
	v_readlane_b32 s13, v242, 10
	s_and_b64 s[10:11], s[12:13], s[10:11]
	s_mov_b64 s[38:39], -1
	s_and_b64 vcc, exec, s[10:11]
	s_movk_i32 s12, 0x2020
	s_cbranch_vccnz .LBB1_1291
	v_or_b32_e32 v128, s6, v139
	v_add_u32_e32 v132, s8, v128
	v_lshl_or_b32 v128, v140, 2, s30
	v_or_b32_e32 v130, s7, v128
	v_lshlrev_b32_e32 v134, 5, v132
	s_movk_i32 s8, 0x1fff
	v_ashrrev_i32_e32 v135, 31, v134
	v_cmp_lt_i32_e32 vcc, s8, v130
	s_and_saveexec_b64 s[8:9], vcc
	s_xor_b64 s[40:41], exec, s[8:9]
	s_cbranch_execz .LBB1_1186
	v_cmp_gt_u32_e64 s[38:39], s12, v130
	s_and_saveexec_b64 s[42:43], s[38:39]
	s_cbranch_execz .LBB1_1185
	v_add_u32_e32 v128, 0xffffe000, v130
	v_lshl_add_u64 v[136:137], v[134:135], 2, s[78:79]
	v_lshlrev_b64 v[142:143], 2, v[128:129]
	v_lshl_add_u64 v[136:137], v[136:137], 0, v[142:143]
	v_lshl_add_u64 v[142:143], s[22:23], 0, v[142:143]
	global_load_dwordx4 v[142:145], v[142:143], off
	s_waitcnt vmcnt(0)
	v_pk_add_f32 v[144:145], v[126:127], v[144:145]
	v_pk_add_f32 v[142:143], v[124:125], v[142:143]
	global_store_dwordx4 v[136:137], v[142:145], off
